# phase C token loop rewritten straight-line: all 8 tokens loads issued up front, neighbour rows shared, DPP+permlane wave sums instead of ds_bpermute, masked stores batched
# speedup vs baseline: 1.1552x; 1.0184x over previous
.LBB0_423:
	s_mov_b32 s67, 8
	v_lshl_add_u64 v[94:95], s[14:15], 0, v[22:23]
	v_lshl_add_u64 v[96:97], s[14:15], 0, v[24:25]
	v_lshl_add_u64 v[98:99], s[14:15], 0, v[26:27]
	v_lshl_add_u64 v[100:101], s[14:15], 0, v[20:21]
	v_lshl_add_u64 v[104:105], s[14:15], 0, v[18:19]
	v_cmp_ge_i32_e64 s[46:47], s60, v16
	v_add_co_u32_e32 v94, vcc, 0x37f0000, v94
	s_nop 1
	v_addc_co_u32_e32 v95, vcc, 0, v95, vcc
	v_add_co_u32_e32 v100, vcc, s61, v100
	s_nop 1
	v_addc_co_u32_e32 v101, vcc, 0, v101, vcc
	s_and_b64 vcc, s[46:47], s[4:5]
	s_and_saveexec_b64 s[6:7], vcc
	s_cbranch_execz .Lcph_c0_nokpe
	global_load_ushort v160, v[98:99], off
	v_lshl_add_u64 v[98:99], v[98:99], 0, s[44:45]
	global_load_ushort v161, v[98:99], off
	v_lshl_add_u64 v[98:99], v[98:99], 0, s[44:45]
	global_load_ushort v162, v[98:99], off
	v_lshl_add_u64 v[98:99], v[98:99], 0, s[44:45]
	global_load_ushort v163, v[98:99], off
	v_lshl_add_u64 v[98:99], v[98:99], 0, s[44:45]
	global_load_ushort v164, v[98:99], off
	v_lshl_add_u64 v[98:99], v[98:99], 0, s[44:45]
	global_load_ushort v165, v[98:99], off
	v_lshl_add_u64 v[98:99], v[98:99], 0, s[44:45]
	global_load_ushort v166, v[98:99], off
	v_lshl_add_u64 v[98:99], v[98:99], 0, s[44:45]
	global_load_ushort v167, v[98:99], off
.Lcph_c0_nokpe:
	s_mov_b64 exec, s[6:7]
	global_load_dwordx2 v[106:107], v[6:7], off
	global_load_dwordx4 v[112:115], v[10:11], off offset:1024
	global_load_dwordx4 v[108:111], v[10:11], off
	global_load_dwordx4 v[116:119], v[10:11], off offset:2048
	global_load_dwordx2 v[168:169], v[94:95], off offset:-3072
	global_load_dwordx2 v[188:189], v[94:95], off offset:-2560
	global_load_dwordx2 v[120:121], v[94:95], off
	global_load_dword v152, v[96:97], off
	global_load_dwordx2 v[136:137], v[94:95], off offset:832
	global_load_dwordx2 v[170:171], v[94:95], off offset:1344
	global_load_dwordx2 v[190:191], v[94:95], off offset:1856
	v_lshl_add_u64 v[94:95], v[94:95], 0, s[44:45]
	v_lshl_add_u64 v[96:97], v[96:97], 0, s[44:45]
	global_load_dwordx2 v[122:123], v[94:95], off
	global_load_dword v153, v[96:97], off
	global_load_dwordx2 v[138:139], v[94:95], off offset:832
	global_load_dwordx2 v[172:173], v[94:95], off offset:1344
	global_load_dwordx2 v[192:193], v[94:95], off offset:1856
	v_lshl_add_u64 v[94:95], v[94:95], 0, s[44:45]
	v_lshl_add_u64 v[96:97], v[96:97], 0, s[44:45]
	global_load_dwordx2 v[124:125], v[94:95], off
	global_load_dword v154, v[96:97], off
	global_load_dwordx2 v[140:141], v[94:95], off offset:832
	global_load_dwordx2 v[174:175], v[94:95], off offset:1344
	global_load_dwordx2 v[194:195], v[94:95], off offset:1856
	v_lshl_add_u64 v[94:95], v[94:95], 0, s[44:45]
	v_lshl_add_u64 v[96:97], v[96:97], 0, s[44:45]
	global_load_dwordx2 v[126:127], v[94:95], off
	global_load_dword v155, v[96:97], off
	global_load_dwordx2 v[142:143], v[94:95], off offset:832
	global_load_dwordx2 v[176:177], v[94:95], off offset:1344
	global_load_dwordx2 v[196:197], v[94:95], off offset:1856
	v_lshl_add_u64 v[94:95], v[94:95], 0, s[44:45]
	v_lshl_add_u64 v[96:97], v[96:97], 0, s[44:45]
	global_load_dwordx2 v[128:129], v[94:95], off
	global_load_dword v156, v[96:97], off
	global_load_dwordx2 v[144:145], v[94:95], off offset:832
	global_load_dwordx2 v[178:179], v[94:95], off offset:1344
	global_load_dwordx2 v[198:199], v[94:95], off offset:1856
	v_lshl_add_u64 v[94:95], v[94:95], 0, s[44:45]
	v_lshl_add_u64 v[96:97], v[96:97], 0, s[44:45]
	global_load_dwordx2 v[130:131], v[94:95], off
	global_load_dword v157, v[96:97], off
	global_load_dwordx2 v[146:147], v[94:95], off offset:832
	global_load_dwordx2 v[180:181], v[94:95], off offset:1344
	global_load_dwordx2 v[200:201], v[94:95], off offset:1856
	v_lshl_add_u64 v[94:95], v[94:95], 0, s[44:45]
	v_lshl_add_u64 v[96:97], v[96:97], 0, s[44:45]
	global_load_dwordx2 v[132:133], v[94:95], off
	global_load_dword v158, v[96:97], off
	global_load_dwordx2 v[148:149], v[94:95], off offset:832
	global_load_dwordx2 v[182:183], v[94:95], off offset:1344
	global_load_dwordx2 v[202:203], v[94:95], off offset:1856
	v_lshl_add_u64 v[94:95], v[94:95], 0, s[44:45]
	v_lshl_add_u64 v[96:97], v[96:97], 0, s[44:45]
	global_load_dwordx2 v[134:135], v[94:95], off
	global_load_dword v159, v[96:97], off
	global_load_dwordx2 v[150:151], v[94:95], off offset:832
	global_load_dwordx2 v[184:185], v[94:95], off offset:1344
	global_load_dwordx2 v[204:205], v[94:95], off offset:1856
	v_lshl_add_u64 v[94:95], v[94:95], 0, s[44:45]
	global_load_dwordx2 v[186:187], v[94:95], off offset:1344
	global_load_dwordx2 v[206:207], v[94:95], off offset:1856
	v_cndmask_b32_e64 v230, v66, 0, s[46:47]
	v_add_u32_e32 v230, v16, v230
	v_ashrrev_i32_e32 v231, 31, v230
	v_lshlrev_b64 v[102:103], 8, v[230:231]
	v_lshl_add_u64 v[102:103], v[8:9], 0, v[102:103]
	s_waitcnt vmcnt(40)
	v_and_b32_e32 v213, 0xffff0000, v120
	v_lshlrev_b32_e32 v212, 16, v120
	v_mul_f32_e32 v208, v213, v213
	v_lshlrev_b32_e32 v214, 16, v121
	v_fmac_f32_e32 v208, v212, v212
	v_and_b32_e32 v215, 0xffff0000, v121
	v_fmac_f32_e32 v208, v214, v214
	v_fmac_f32_e32 v208, v215, v215
	v_lshlrev_b32_e32 v216, 16, v152
	v_and_b32_e32 v217, 0xffff0000, v152
	v_mul_f32_e32 v212, v216, v216
	v_mul_f32_e32 v213, v217, v217
	v_add_f32_e32 v209, v212, v213
	s_nop 0
	v_add_f32_dpp v208, v208, v208 quad_perm:[1,0,3,2] row_mask:0xf bank_mask:0xf
	v_add_f32_dpp v209, v209, v209 quad_perm:[1,0,3,2] row_mask:0xf bank_mask:0xf
	s_nop 0
	v_add_f32_dpp v208, v208, v208 quad_perm:[2,3,0,1] row_mask:0xf bank_mask:0xf
	v_add_f32_dpp v209, v209, v209 quad_perm:[2,3,0,1] row_mask:0xf bank_mask:0xf
	s_nop 0
	v_add_f32_dpp v208, v208, v208 row_half_mirror row_mask:0xf bank_mask:0xf
	v_add_f32_dpp v209, v209, v209 row_half_mirror row_mask:0xf bank_mask:0xf
	s_nop 0
	v_add_f32_dpp v208, v208, v208 row_mirror row_mask:0xf bank_mask:0xf
	v_add_f32_dpp v209, v209, v209 row_mirror row_mask:0xf bank_mask:0xf
	s_nop 0
	v_mov_b32_e32 v210, v208
	v_mov_b32_e32 v211, v209
	s_nop 1
	v_permlane32_swap_b32_e32 v208, v210
	v_permlane32_swap_b32_e32 v209, v211
	s_nop 0
	v_add_f32_e32 v208, v208, v210
	v_add_f32_e32 v209, v209, v211
	v_mov_b32_e32 v210, v208
	v_mov_b32_e32 v211, v209
	s_nop 1
	v_permlane16_swap_b32_e32 v208, v210
	v_permlane16_swap_b32_e32 v209, v211
	s_nop 0
	v_add_f32_e32 v208, v208, v210
	v_add_f32_e32 v209, v209, v211
	v_fmamk_f32 v152, v208, 0x3b800000, v48
	v_fmamk_f32 v209, v209, 0x3c000000, v48
	v_mul_f32_e32 v212, 0x4b800000, v209
	v_cmp_gt_f32_e64 s[6:7], s59, v209
	s_nop 1
	v_cndmask_b32_e64 v209, v209, v212, s[6:7]
	v_rsq_f32_e32 v209, v209
	s_nop 0
	v_mul_f32_e32 v212, 0x45800000, v209
	v_cndmask_b32_e64 v209, v209, v212, s[6:7]
	v_mul_f32_e32 v216, v209, v216
	v_mul_f32_e32 v217, v209, v217
	v_mul_f32_e32 v120, v106, v216
	v_mul_f32_e32 v121, v107, v217
	v_cvt_pk_bf16_f32 v212, v120, v121
	global_store_dword v[102:103], v212, off
	s_waitcnt vmcnt(33)
	v_lshlrev_b32_e32 v224, 16, v168
	v_lshlrev_b32_e32 v225, 16, v188
	v_and_b32_e32 v168, 0xffff0000, v168
	v_and_b32_e32 v188, 0xffff0000, v188
	v_mul_f32_e32 v188, v168, v188
	v_mul_f32_e32 v168, v224, v225
	v_lshlrev_b32_e32 v224, 16, v169
	v_lshlrev_b32_e32 v225, 16, v189
	v_and_b32_e32 v169, 0xffff0000, v169
	v_and_b32_e32 v189, 0xffff0000, v189
	v_mul_f32_e32 v189, v169, v189
	v_mul_f32_e32 v169, v224, v225
	v_lshlrev_b32_e32 v224, 16, v170
	v_lshlrev_b32_e32 v225, 16, v190
	v_and_b32_e32 v170, 0xffff0000, v170
	v_and_b32_e32 v190, 0xffff0000, v190
	v_mul_f32_e32 v190, v170, v190
	v_mul_f32_e32 v170, v224, v225
	v_lshlrev_b32_e32 v224, 16, v171
	v_lshlrev_b32_e32 v225, 16, v191
	v_and_b32_e32 v171, 0xffff0000, v171
	v_and_b32_e32 v191, 0xffff0000, v191
	v_mul_f32_e32 v191, v171, v191
	v_mul_f32_e32 v171, v224, v225
	v_and_b32_e32 v226, 0xff, v67
	v_cndmask_b32_e64 v226, v68, v226, s[46:47]
	v_cmp_ne_u32_e32 vcc, 0, v226
	s_nop 1
	v_cndmask_b32_e32 v168, 0, v168, vcc
	v_cndmask_b32_e32 v188, 0, v188, vcc
	v_cndmask_b32_e32 v169, 0, v169, vcc
	v_cndmask_b32_e32 v189, 0, v189, vcc
	v_lshlrev_b32_e32 v224, 16, v172
	v_lshlrev_b32_e32 v225, 16, v192
	v_and_b32_e32 v172, 0xffff0000, v172
	v_and_b32_e32 v192, 0xffff0000, v192
	v_mul_f32_e32 v192, v172, v192
	v_mul_f32_e32 v172, v224, v225
	v_lshlrev_b32_e32 v224, 16, v173
	v_lshlrev_b32_e32 v225, 16, v193
	v_and_b32_e32 v173, 0xffff0000, v173
	v_and_b32_e32 v193, 0xffff0000, v193
	v_mul_f32_e32 v193, v173, v193
	v_mul_f32_e32 v173, v224, v225
	v_mul_f32_e32 v218, v170, v112
	v_mul_f32_e32 v219, v190, v113
	v_mul_f32_e32 v220, v171, v114
	v_mul_f32_e32 v221, v191, v115
	v_fmac_f32_e32 v218, v168, v108
	v_fmac_f32_e32 v219, v188, v109
	v_fmac_f32_e32 v220, v169, v110
	v_fmac_f32_e32 v221, v189, v111
	v_fmac_f32_e32 v218, v172, v116
	v_fmac_f32_e32 v219, v192, v117
	v_fmac_f32_e32 v220, v173, v118
	v_fmac_f32_e32 v221, v193, v119
	v_lshlrev_b32_e32 v212, 16, v136
	v_and_b32_e32 v213, 0xffff0000, v136
	v_lshlrev_b32_e32 v214, 16, v137
	v_and_b32_e32 v215, 0xffff0000, v137
	v_mul_f32_e32 v218, v218, v212
	v_mul_f32_e32 v219, v219, v213
	v_mul_f32_e32 v220, v220, v214
	v_mul_f32_e32 v221, v221, v215
	v_cvt_pk_bf16_f32 v222, v218, v219
	v_cvt_pk_bf16_f32 v223, v220, v221
	global_store_dwordx2 v[100:101], v[222:223], off offset:1024
	v_lshl_add_u64 v[100:101], v[100:101], 0, s[42:43]
	s_waitcnt vmcnt(37)
	v_and_b32_e32 v213, 0xffff0000, v122
	v_lshlrev_b32_e32 v212, 16, v122
	v_mul_f32_e32 v208, v213, v213
	v_lshlrev_b32_e32 v214, 16, v123
	v_fmac_f32_e32 v208, v212, v212
	v_and_b32_e32 v215, 0xffff0000, v123
	v_fmac_f32_e32 v208, v214, v214
	v_fmac_f32_e32 v208, v215, v215
	v_lshlrev_b32_e32 v216, 16, v153
	v_and_b32_e32 v217, 0xffff0000, v153
	v_mul_f32_e32 v212, v216, v216
	v_mul_f32_e32 v213, v217, v217
	v_add_f32_e32 v209, v212, v213
	s_nop 0
	v_add_f32_dpp v208, v208, v208 quad_perm:[1,0,3,2] row_mask:0xf bank_mask:0xf
	v_add_f32_dpp v209, v209, v209 quad_perm:[1,0,3,2] row_mask:0xf bank_mask:0xf
	s_nop 0
	v_add_f32_dpp v208, v208, v208 quad_perm:[2,3,0,1] row_mask:0xf bank_mask:0xf
	v_add_f32_dpp v209, v209, v209 quad_perm:[2,3,0,1] row_mask:0xf bank_mask:0xf
	s_nop 0
	v_add_f32_dpp v208, v208, v208 row_half_mirror row_mask:0xf bank_mask:0xf
	v_add_f32_dpp v209, v209, v209 row_half_mirror row_mask:0xf bank_mask:0xf
	s_nop 0
	v_add_f32_dpp v208, v208, v208 row_mirror row_mask:0xf bank_mask:0xf
	v_add_f32_dpp v209, v209, v209 row_mirror row_mask:0xf bank_mask:0xf
	s_nop 0
	v_mov_b32_e32 v210, v208
	v_mov_b32_e32 v211, v209
	s_nop 1
	v_permlane32_swap_b32_e32 v208, v210
	v_permlane32_swap_b32_e32 v209, v211
	s_nop 0
	v_add_f32_e32 v208, v208, v210
	v_add_f32_e32 v209, v209, v211
	v_mov_b32_e32 v210, v208
	v_mov_b32_e32 v211, v209
	s_nop 1
	v_permlane16_swap_b32_e32 v208, v210
	v_permlane16_swap_b32_e32 v209, v211
	s_nop 0
	v_add_f32_e32 v208, v208, v210
	v_add_f32_e32 v209, v209, v211
	v_fmamk_f32 v153, v208, 0x3b800000, v48
	v_fmamk_f32 v209, v209, 0x3c000000, v48
	v_mul_f32_e32 v212, 0x4b800000, v209
	v_cmp_gt_f32_e64 s[6:7], s59, v209
	s_nop 1
	v_cndmask_b32_e64 v209, v209, v212, s[6:7]
	v_rsq_f32_e32 v209, v209
	s_nop 0
	v_mul_f32_e32 v212, 0x45800000, v209
	v_cndmask_b32_e64 v209, v209, v212, s[6:7]
	v_mul_f32_e32 v216, v209, v216
	v_mul_f32_e32 v217, v209, v217
	v_mul_f32_e32 v122, v106, v216
	v_mul_f32_e32 v123, v107, v217
	v_cvt_pk_bf16_f32 v212, v122, v123
	global_store_dword v[102:103], v212, off offset:256
	s_waitcnt vmcnt(30)
	v_lshlrev_b32_e32 v224, 16, v174
	v_lshlrev_b32_e32 v225, 16, v194
	v_and_b32_e32 v174, 0xffff0000, v174
	v_and_b32_e32 v194, 0xffff0000, v194
	v_mul_f32_e32 v194, v174, v194
	v_mul_f32_e32 v174, v224, v225
	v_lshlrev_b32_e32 v224, 16, v175
	v_lshlrev_b32_e32 v225, 16, v195
	v_and_b32_e32 v175, 0xffff0000, v175
	v_and_b32_e32 v195, 0xffff0000, v195
	v_mul_f32_e32 v195, v175, v195
	v_mul_f32_e32 v175, v224, v225
	v_mul_f32_e32 v218, v172, v112
	v_mul_f32_e32 v219, v192, v113
	v_mul_f32_e32 v220, v173, v114
	v_mul_f32_e32 v221, v193, v115
	v_fmac_f32_e32 v218, v170, v108
	v_fmac_f32_e32 v219, v190, v109
	v_fmac_f32_e32 v220, v171, v110
	v_fmac_f32_e32 v221, v191, v111
	v_fmac_f32_e32 v218, v174, v116
	v_fmac_f32_e32 v219, v194, v117
	v_fmac_f32_e32 v220, v175, v118
	v_fmac_f32_e32 v221, v195, v119
	v_lshlrev_b32_e32 v212, 16, v138
	v_and_b32_e32 v213, 0xffff0000, v138
	v_lshlrev_b32_e32 v214, 16, v139
	v_and_b32_e32 v215, 0xffff0000, v139
	v_mul_f32_e32 v218, v218, v212
	v_mul_f32_e32 v219, v219, v213
	v_mul_f32_e32 v220, v220, v214
	v_mul_f32_e32 v221, v221, v215
	v_cvt_pk_bf16_f32 v222, v218, v219
	v_cvt_pk_bf16_f32 v223, v220, v221
	global_store_dwordx2 v[100:101], v[222:223], off offset:1024
	v_lshl_add_u64 v[100:101], v[100:101], 0, s[42:43]
	s_waitcnt vmcnt(34)
	v_and_b32_e32 v213, 0xffff0000, v124
	v_lshlrev_b32_e32 v212, 16, v124
	v_mul_f32_e32 v208, v213, v213
	v_lshlrev_b32_e32 v214, 16, v125
	v_fmac_f32_e32 v208, v212, v212
	v_and_b32_e32 v215, 0xffff0000, v125
	v_fmac_f32_e32 v208, v214, v214
	v_fmac_f32_e32 v208, v215, v215
	v_lshlrev_b32_e32 v216, 16, v154
	v_and_b32_e32 v217, 0xffff0000, v154
	v_mul_f32_e32 v212, v216, v216
	v_mul_f32_e32 v213, v217, v217
	v_add_f32_e32 v209, v212, v213
	s_nop 0
	v_add_f32_dpp v208, v208, v208 quad_perm:[1,0,3,2] row_mask:0xf bank_mask:0xf
	v_add_f32_dpp v209, v209, v209 quad_perm:[1,0,3,2] row_mask:0xf bank_mask:0xf
	s_nop 0
	v_add_f32_dpp v208, v208, v208 quad_perm:[2,3,0,1] row_mask:0xf bank_mask:0xf
	v_add_f32_dpp v209, v209, v209 quad_perm:[2,3,0,1] row_mask:0xf bank_mask:0xf
	s_nop 0
	v_add_f32_dpp v208, v208, v208 row_half_mirror row_mask:0xf bank_mask:0xf
	v_add_f32_dpp v209, v209, v209 row_half_mirror row_mask:0xf bank_mask:0xf
	s_nop 0
	v_add_f32_dpp v208, v208, v208 row_mirror row_mask:0xf bank_mask:0xf
	v_add_f32_dpp v209, v209, v209 row_mirror row_mask:0xf bank_mask:0xf
	s_nop 0
	v_mov_b32_e32 v210, v208
	v_mov_b32_e32 v211, v209
	s_nop 1
	v_permlane32_swap_b32_e32 v208, v210
	v_permlane32_swap_b32_e32 v209, v211
	s_nop 0
	v_add_f32_e32 v208, v208, v210
	v_add_f32_e32 v209, v209, v211
	v_mov_b32_e32 v210, v208
	v_mov_b32_e32 v211, v209
	s_nop 1
	v_permlane16_swap_b32_e32 v208, v210
	v_permlane16_swap_b32_e32 v209, v211
	s_nop 0
	v_add_f32_e32 v208, v208, v210
	v_add_f32_e32 v209, v209, v211
	v_fmamk_f32 v154, v208, 0x3b800000, v48
	v_fmamk_f32 v209, v209, 0x3c000000, v48
	v_mul_f32_e32 v212, 0x4b800000, v209
	v_cmp_gt_f32_e64 s[6:7], s59, v209
	s_nop 1
	v_cndmask_b32_e64 v209, v209, v212, s[6:7]
	v_rsq_f32_e32 v209, v209
	s_nop 0
	v_mul_f32_e32 v212, 0x45800000, v209
	v_cndmask_b32_e64 v209, v209, v212, s[6:7]
	v_mul_f32_e32 v216, v209, v216
	v_mul_f32_e32 v217, v209, v217
	v_mul_f32_e32 v124, v106, v216
	v_mul_f32_e32 v125, v107, v217
	v_cvt_pk_bf16_f32 v212, v124, v125
	global_store_dword v[102:103], v212, off offset:512
	s_waitcnt vmcnt(27)
	v_lshlrev_b32_e32 v224, 16, v176
	v_lshlrev_b32_e32 v225, 16, v196
	v_and_b32_e32 v176, 0xffff0000, v176
	v_and_b32_e32 v196, 0xffff0000, v196
	v_mul_f32_e32 v196, v176, v196
	v_mul_f32_e32 v176, v224, v225
	v_lshlrev_b32_e32 v224, 16, v177
	v_lshlrev_b32_e32 v225, 16, v197
	v_and_b32_e32 v177, 0xffff0000, v177
	v_and_b32_e32 v197, 0xffff0000, v197
	v_mul_f32_e32 v197, v177, v197
	v_mul_f32_e32 v177, v224, v225
	v_mul_f32_e32 v218, v174, v112
	v_mul_f32_e32 v219, v194, v113
	v_mul_f32_e32 v220, v175, v114
	v_mul_f32_e32 v221, v195, v115
	v_fmac_f32_e32 v218, v172, v108
	v_fmac_f32_e32 v219, v192, v109
	v_fmac_f32_e32 v220, v173, v110
	v_fmac_f32_e32 v221, v193, v111
	v_fmac_f32_e32 v218, v176, v116
	v_fmac_f32_e32 v219, v196, v117
	v_fmac_f32_e32 v220, v177, v118
	v_fmac_f32_e32 v221, v197, v119
	v_lshlrev_b32_e32 v212, 16, v140
	v_and_b32_e32 v213, 0xffff0000, v140
	v_lshlrev_b32_e32 v214, 16, v141
	v_and_b32_e32 v215, 0xffff0000, v141
	v_mul_f32_e32 v218, v218, v212
	v_mul_f32_e32 v219, v219, v213
	v_mul_f32_e32 v220, v220, v214
	v_mul_f32_e32 v221, v221, v215
	v_cvt_pk_bf16_f32 v222, v218, v219
	v_cvt_pk_bf16_f32 v223, v220, v221
	global_store_dwordx2 v[100:101], v[222:223], off offset:1024
	v_lshl_add_u64 v[100:101], v[100:101], 0, s[42:43]
	s_waitcnt vmcnt(31)
	v_and_b32_e32 v213, 0xffff0000, v126
	v_lshlrev_b32_e32 v212, 16, v126
	v_mul_f32_e32 v208, v213, v213
	v_lshlrev_b32_e32 v214, 16, v127
	v_fmac_f32_e32 v208, v212, v212
	v_and_b32_e32 v215, 0xffff0000, v127
	v_fmac_f32_e32 v208, v214, v214
	v_fmac_f32_e32 v208, v215, v215
	v_lshlrev_b32_e32 v216, 16, v155
	v_and_b32_e32 v217, 0xffff0000, v155
	v_mul_f32_e32 v212, v216, v216
	v_mul_f32_e32 v213, v217, v217
	v_add_f32_e32 v209, v212, v213
	s_nop 0
	v_add_f32_dpp v208, v208, v208 quad_perm:[1,0,3,2] row_mask:0xf bank_mask:0xf
	v_add_f32_dpp v209, v209, v209 quad_perm:[1,0,3,2] row_mask:0xf bank_mask:0xf
	s_nop 0
	v_add_f32_dpp v208, v208, v208 quad_perm:[2,3,0,1] row_mask:0xf bank_mask:0xf
	v_add_f32_dpp v209, v209, v209 quad_perm:[2,3,0,1] row_mask:0xf bank_mask:0xf
	s_nop 0
	v_add_f32_dpp v208, v208, v208 row_half_mirror row_mask:0xf bank_mask:0xf
	v_add_f32_dpp v209, v209, v209 row_half_mirror row_mask:0xf bank_mask:0xf
	s_nop 0
	v_add_f32_dpp v208, v208, v208 row_mirror row_mask:0xf bank_mask:0xf
	v_add_f32_dpp v209, v209, v209 row_mirror row_mask:0xf bank_mask:0xf
	s_nop 0
	v_mov_b32_e32 v210, v208
	v_mov_b32_e32 v211, v209
	s_nop 1
	v_permlane32_swap_b32_e32 v208, v210
	v_permlane32_swap_b32_e32 v209, v211
	s_nop 0
	v_add_f32_e32 v208, v208, v210
	v_add_f32_e32 v209, v209, v211
	v_mov_b32_e32 v210, v208
	v_mov_b32_e32 v211, v209
	s_nop 1
	v_permlane16_swap_b32_e32 v208, v210
	v_permlane16_swap_b32_e32 v209, v211
	s_nop 0
	v_add_f32_e32 v208, v208, v210
	v_add_f32_e32 v209, v209, v211
	v_fmamk_f32 v155, v208, 0x3b800000, v48
	v_fmamk_f32 v209, v209, 0x3c000000, v48
	v_mul_f32_e32 v212, 0x4b800000, v209
	v_cmp_gt_f32_e64 s[6:7], s59, v209
	s_nop 1
	v_cndmask_b32_e64 v209, v209, v212, s[6:7]
	v_rsq_f32_e32 v209, v209
	s_nop 0
	v_mul_f32_e32 v212, 0x45800000, v209
	v_cndmask_b32_e64 v209, v209, v212, s[6:7]
	v_mul_f32_e32 v216, v209, v216
	v_mul_f32_e32 v217, v209, v217
	v_mul_f32_e32 v126, v106, v216
	v_mul_f32_e32 v127, v107, v217
	v_cvt_pk_bf16_f32 v212, v126, v127
	global_store_dword v[102:103], v212, off offset:768
	s_waitcnt vmcnt(24)
	v_lshlrev_b32_e32 v224, 16, v178
	v_lshlrev_b32_e32 v225, 16, v198
	v_and_b32_e32 v178, 0xffff0000, v178
	v_and_b32_e32 v198, 0xffff0000, v198
	v_mul_f32_e32 v198, v178, v198
	v_mul_f32_e32 v178, v224, v225
	v_lshlrev_b32_e32 v224, 16, v179
	v_lshlrev_b32_e32 v225, 16, v199
	v_and_b32_e32 v179, 0xffff0000, v179
	v_and_b32_e32 v199, 0xffff0000, v199
	v_mul_f32_e32 v199, v179, v199
	v_mul_f32_e32 v179, v224, v225
	v_mul_f32_e32 v218, v176, v112
	v_mul_f32_e32 v219, v196, v113
	v_mul_f32_e32 v220, v177, v114
	v_mul_f32_e32 v221, v197, v115
	v_fmac_f32_e32 v218, v174, v108
	v_fmac_f32_e32 v219, v194, v109
	v_fmac_f32_e32 v220, v175, v110
	v_fmac_f32_e32 v221, v195, v111
	v_fmac_f32_e32 v218, v178, v116
	v_fmac_f32_e32 v219, v198, v117
	v_fmac_f32_e32 v220, v179, v118
	v_fmac_f32_e32 v221, v199, v119
	v_lshlrev_b32_e32 v212, 16, v142
	v_and_b32_e32 v213, 0xffff0000, v142
	v_lshlrev_b32_e32 v214, 16, v143
	v_and_b32_e32 v215, 0xffff0000, v143
	v_mul_f32_e32 v218, v218, v212
	v_mul_f32_e32 v219, v219, v213
	v_mul_f32_e32 v220, v220, v214
	v_mul_f32_e32 v221, v221, v215
	v_cvt_pk_bf16_f32 v222, v218, v219
	v_cvt_pk_bf16_f32 v223, v220, v221
	global_store_dwordx2 v[100:101], v[222:223], off offset:1024
	v_lshl_add_u64 v[100:101], v[100:101], 0, s[42:43]
	s_waitcnt vmcnt(28)
	v_and_b32_e32 v213, 0xffff0000, v128
	v_lshlrev_b32_e32 v212, 16, v128
	v_mul_f32_e32 v208, v213, v213
	v_lshlrev_b32_e32 v214, 16, v129
	v_fmac_f32_e32 v208, v212, v212
	v_and_b32_e32 v215, 0xffff0000, v129
	v_fmac_f32_e32 v208, v214, v214
	v_fmac_f32_e32 v208, v215, v215
	v_lshlrev_b32_e32 v216, 16, v156
	v_and_b32_e32 v217, 0xffff0000, v156
	v_mul_f32_e32 v212, v216, v216
	v_mul_f32_e32 v213, v217, v217
	v_add_f32_e32 v209, v212, v213
	s_nop 0
	v_add_f32_dpp v208, v208, v208 quad_perm:[1,0,3,2] row_mask:0xf bank_mask:0xf
	v_add_f32_dpp v209, v209, v209 quad_perm:[1,0,3,2] row_mask:0xf bank_mask:0xf
	s_nop 0
	v_add_f32_dpp v208, v208, v208 quad_perm:[2,3,0,1] row_mask:0xf bank_mask:0xf
	v_add_f32_dpp v209, v209, v209 quad_perm:[2,3,0,1] row_mask:0xf bank_mask:0xf
	s_nop 0
	v_add_f32_dpp v208, v208, v208 row_half_mirror row_mask:0xf bank_mask:0xf
	v_add_f32_dpp v209, v209, v209 row_half_mirror row_mask:0xf bank_mask:0xf
	s_nop 0
	v_add_f32_dpp v208, v208, v208 row_mirror row_mask:0xf bank_mask:0xf
	v_add_f32_dpp v209, v209, v209 row_mirror row_mask:0xf bank_mask:0xf
	s_nop 0
	v_mov_b32_e32 v210, v208
	v_mov_b32_e32 v211, v209
	s_nop 1
	v_permlane32_swap_b32_e32 v208, v210
	v_permlane32_swap_b32_e32 v209, v211
	s_nop 0
	v_add_f32_e32 v208, v208, v210
	v_add_f32_e32 v209, v209, v211
	v_mov_b32_e32 v210, v208
	v_mov_b32_e32 v211, v209
	s_nop 1
	v_permlane16_swap_b32_e32 v208, v210
	v_permlane16_swap_b32_e32 v209, v211
	s_nop 0
	v_add_f32_e32 v208, v208, v210
	v_add_f32_e32 v209, v209, v211
	v_fmamk_f32 v156, v208, 0x3b800000, v48
	v_fmamk_f32 v209, v209, 0x3c000000, v48
	v_mul_f32_e32 v212, 0x4b800000, v209
	v_cmp_gt_f32_e64 s[6:7], s59, v209
	s_nop 1
	v_cndmask_b32_e64 v209, v209, v212, s[6:7]
	v_rsq_f32_e32 v209, v209
	s_nop 0
	v_mul_f32_e32 v212, 0x45800000, v209
	v_cndmask_b32_e64 v209, v209, v212, s[6:7]
	v_mul_f32_e32 v216, v209, v216
	v_mul_f32_e32 v217, v209, v217
	v_mul_f32_e32 v128, v106, v216
	v_mul_f32_e32 v129, v107, v217
	v_cvt_pk_bf16_f32 v212, v128, v129
	global_store_dword v[102:103], v212, off offset:1024
	s_waitcnt vmcnt(21)
	v_lshlrev_b32_e32 v224, 16, v180
	v_lshlrev_b32_e32 v225, 16, v200
	v_and_b32_e32 v180, 0xffff0000, v180
	v_and_b32_e32 v200, 0xffff0000, v200
	v_mul_f32_e32 v200, v180, v200
	v_mul_f32_e32 v180, v224, v225
	v_lshlrev_b32_e32 v224, 16, v181
	v_lshlrev_b32_e32 v225, 16, v201
	v_and_b32_e32 v181, 0xffff0000, v181
	v_and_b32_e32 v201, 0xffff0000, v201
	v_mul_f32_e32 v201, v181, v201
	v_mul_f32_e32 v181, v224, v225
	v_mul_f32_e32 v218, v178, v112
	v_mul_f32_e32 v219, v198, v113
	v_mul_f32_e32 v220, v179, v114
	v_mul_f32_e32 v221, v199, v115
	v_fmac_f32_e32 v218, v176, v108
	v_fmac_f32_e32 v219, v196, v109
	v_fmac_f32_e32 v220, v177, v110
	v_fmac_f32_e32 v221, v197, v111
	v_fmac_f32_e32 v218, v180, v116
	v_fmac_f32_e32 v219, v200, v117
	v_fmac_f32_e32 v220, v181, v118
	v_fmac_f32_e32 v221, v201, v119
	v_lshlrev_b32_e32 v212, 16, v144
	v_and_b32_e32 v213, 0xffff0000, v144
	v_lshlrev_b32_e32 v214, 16, v145
	v_and_b32_e32 v215, 0xffff0000, v145
	v_mul_f32_e32 v218, v218, v212
	v_mul_f32_e32 v219, v219, v213
	v_mul_f32_e32 v220, v220, v214
	v_mul_f32_e32 v221, v221, v215
	v_cvt_pk_bf16_f32 v222, v218, v219
	v_cvt_pk_bf16_f32 v223, v220, v221
	global_store_dwordx2 v[100:101], v[222:223], off offset:1024
	v_lshl_add_u64 v[100:101], v[100:101], 0, s[42:43]
	s_waitcnt vmcnt(25)
	v_and_b32_e32 v213, 0xffff0000, v130
	v_lshlrev_b32_e32 v212, 16, v130
	v_mul_f32_e32 v208, v213, v213
	v_lshlrev_b32_e32 v214, 16, v131
	v_fmac_f32_e32 v208, v212, v212
	v_and_b32_e32 v215, 0xffff0000, v131
	v_fmac_f32_e32 v208, v214, v214
	v_fmac_f32_e32 v208, v215, v215
	v_lshlrev_b32_e32 v216, 16, v157
	v_and_b32_e32 v217, 0xffff0000, v157
	v_mul_f32_e32 v212, v216, v216
	v_mul_f32_e32 v213, v217, v217
	v_add_f32_e32 v209, v212, v213
	s_nop 0
	v_add_f32_dpp v208, v208, v208 quad_perm:[1,0,3,2] row_mask:0xf bank_mask:0xf
	v_add_f32_dpp v209, v209, v209 quad_perm:[1,0,3,2] row_mask:0xf bank_mask:0xf
	s_nop 0
	v_add_f32_dpp v208, v208, v208 quad_perm:[2,3,0,1] row_mask:0xf bank_mask:0xf
	v_add_f32_dpp v209, v209, v209 quad_perm:[2,3,0,1] row_mask:0xf bank_mask:0xf
	s_nop 0
	v_add_f32_dpp v208, v208, v208 row_half_mirror row_mask:0xf bank_mask:0xf
	v_add_f32_dpp v209, v209, v209 row_half_mirror row_mask:0xf bank_mask:0xf
	s_nop 0
	v_add_f32_dpp v208, v208, v208 row_mirror row_mask:0xf bank_mask:0xf
	v_add_f32_dpp v209, v209, v209 row_mirror row_mask:0xf bank_mask:0xf
	s_nop 0
	v_mov_b32_e32 v210, v208
	v_mov_b32_e32 v211, v209
	s_nop 1
	v_permlane32_swap_b32_e32 v208, v210
	v_permlane32_swap_b32_e32 v209, v211
	s_nop 0
	v_add_f32_e32 v208, v208, v210
	v_add_f32_e32 v209, v209, v211
	v_mov_b32_e32 v210, v208
	v_mov_b32_e32 v211, v209
	s_nop 1
	v_permlane16_swap_b32_e32 v208, v210
	v_permlane16_swap_b32_e32 v209, v211
	s_nop 0
	v_add_f32_e32 v208, v208, v210
	v_add_f32_e32 v209, v209, v211
	v_fmamk_f32 v157, v208, 0x3b800000, v48
	v_fmamk_f32 v209, v209, 0x3c000000, v48
	v_mul_f32_e32 v212, 0x4b800000, v209
	v_cmp_gt_f32_e64 s[6:7], s59, v209
	s_nop 1
	v_cndmask_b32_e64 v209, v209, v212, s[6:7]
	v_rsq_f32_e32 v209, v209
	s_nop 0
	v_mul_f32_e32 v212, 0x45800000, v209
	v_cndmask_b32_e64 v209, v209, v212, s[6:7]
	v_mul_f32_e32 v216, v209, v216
	v_mul_f32_e32 v217, v209, v217
	v_mul_f32_e32 v130, v106, v216
	v_mul_f32_e32 v131, v107, v217
	v_cvt_pk_bf16_f32 v212, v130, v131
	global_store_dword v[102:103], v212, off offset:1280
	s_waitcnt vmcnt(18)
	v_lshlrev_b32_e32 v224, 16, v182
	v_lshlrev_b32_e32 v225, 16, v202
	v_and_b32_e32 v182, 0xffff0000, v182
	v_and_b32_e32 v202, 0xffff0000, v202
	v_mul_f32_e32 v202, v182, v202
	v_mul_f32_e32 v182, v224, v225
	v_lshlrev_b32_e32 v224, 16, v183
	v_lshlrev_b32_e32 v225, 16, v203
	v_and_b32_e32 v183, 0xffff0000, v183
	v_and_b32_e32 v203, 0xffff0000, v203
	v_mul_f32_e32 v203, v183, v203
	v_mul_f32_e32 v183, v224, v225
	v_mul_f32_e32 v218, v180, v112
	v_mul_f32_e32 v219, v200, v113
	v_mul_f32_e32 v220, v181, v114
	v_mul_f32_e32 v221, v201, v115
	v_fmac_f32_e32 v218, v178, v108
	v_fmac_f32_e32 v219, v198, v109
	v_fmac_f32_e32 v220, v179, v110
	v_fmac_f32_e32 v221, v199, v111
	v_fmac_f32_e32 v218, v182, v116
	v_fmac_f32_e32 v219, v202, v117
	v_fmac_f32_e32 v220, v183, v118
	v_fmac_f32_e32 v221, v203, v119
	v_lshlrev_b32_e32 v212, 16, v146
	v_and_b32_e32 v213, 0xffff0000, v146
	v_lshlrev_b32_e32 v214, 16, v147
	v_and_b32_e32 v215, 0xffff0000, v147
	v_mul_f32_e32 v218, v218, v212
	v_mul_f32_e32 v219, v219, v213
	v_mul_f32_e32 v220, v220, v214
	v_mul_f32_e32 v221, v221, v215
	v_cvt_pk_bf16_f32 v222, v218, v219
	v_cvt_pk_bf16_f32 v223, v220, v221
	global_store_dwordx2 v[100:101], v[222:223], off offset:1024
	v_lshl_add_u64 v[100:101], v[100:101], 0, s[42:43]
	s_waitcnt vmcnt(22)
	v_and_b32_e32 v213, 0xffff0000, v132
	v_lshlrev_b32_e32 v212, 16, v132
	v_mul_f32_e32 v208, v213, v213
	v_lshlrev_b32_e32 v214, 16, v133
	v_fmac_f32_e32 v208, v212, v212
	v_and_b32_e32 v215, 0xffff0000, v133
	v_fmac_f32_e32 v208, v214, v214
	v_fmac_f32_e32 v208, v215, v215
	v_lshlrev_b32_e32 v216, 16, v158
	v_and_b32_e32 v217, 0xffff0000, v158
	v_mul_f32_e32 v212, v216, v216
	v_mul_f32_e32 v213, v217, v217
	v_add_f32_e32 v209, v212, v213
	s_nop 0
	v_add_f32_dpp v208, v208, v208 quad_perm:[1,0,3,2] row_mask:0xf bank_mask:0xf
	v_add_f32_dpp v209, v209, v209 quad_perm:[1,0,3,2] row_mask:0xf bank_mask:0xf
	s_nop 0
	v_add_f32_dpp v208, v208, v208 quad_perm:[2,3,0,1] row_mask:0xf bank_mask:0xf
	v_add_f32_dpp v209, v209, v209 quad_perm:[2,3,0,1] row_mask:0xf bank_mask:0xf
	s_nop 0
	v_add_f32_dpp v208, v208, v208 row_half_mirror row_mask:0xf bank_mask:0xf
	v_add_f32_dpp v209, v209, v209 row_half_mirror row_mask:0xf bank_mask:0xf
	s_nop 0
	v_add_f32_dpp v208, v208, v208 row_mirror row_mask:0xf bank_mask:0xf
	v_add_f32_dpp v209, v209, v209 row_mirror row_mask:0xf bank_mask:0xf
	s_nop 0
	v_mov_b32_e32 v210, v208
	v_mov_b32_e32 v211, v209
	s_nop 1
	v_permlane32_swap_b32_e32 v208, v210
	v_permlane32_swap_b32_e32 v209, v211
	s_nop 0
	v_add_f32_e32 v208, v208, v210
	v_add_f32_e32 v209, v209, v211
	v_mov_b32_e32 v210, v208
	v_mov_b32_e32 v211, v209
	s_nop 1
	v_permlane16_swap_b32_e32 v208, v210
	v_permlane16_swap_b32_e32 v209, v211
	s_nop 0
	v_add_f32_e32 v208, v208, v210
	v_add_f32_e32 v209, v209, v211
	v_fmamk_f32 v158, v208, 0x3b800000, v48
	v_fmamk_f32 v209, v209, 0x3c000000, v48
	v_mul_f32_e32 v212, 0x4b800000, v209
	v_cmp_gt_f32_e64 s[6:7], s59, v209
	s_nop 1
	v_cndmask_b32_e64 v209, v209, v212, s[6:7]
	v_rsq_f32_e32 v209, v209
	s_nop 0
	v_mul_f32_e32 v212, 0x45800000, v209
	v_cndmask_b32_e64 v209, v209, v212, s[6:7]
	v_mul_f32_e32 v216, v209, v216
	v_mul_f32_e32 v217, v209, v217
	v_mul_f32_e32 v132, v106, v216
	v_mul_f32_e32 v133, v107, v217
	v_cvt_pk_bf16_f32 v212, v132, v133
	global_store_dword v[102:103], v212, off offset:1536
	s_waitcnt vmcnt(15)
	v_lshlrev_b32_e32 v224, 16, v184
	v_lshlrev_b32_e32 v225, 16, v204
	v_and_b32_e32 v184, 0xffff0000, v184
	v_and_b32_e32 v204, 0xffff0000, v204
	v_mul_f32_e32 v204, v184, v204
	v_mul_f32_e32 v184, v224, v225
	v_lshlrev_b32_e32 v224, 16, v185
	v_lshlrev_b32_e32 v225, 16, v205
	v_and_b32_e32 v185, 0xffff0000, v185
	v_and_b32_e32 v205, 0xffff0000, v205
	v_mul_f32_e32 v205, v185, v205
	v_mul_f32_e32 v185, v224, v225
	v_mul_f32_e32 v218, v182, v112
	v_mul_f32_e32 v219, v202, v113
	v_mul_f32_e32 v220, v183, v114
	v_mul_f32_e32 v221, v203, v115
	v_fmac_f32_e32 v218, v180, v108
	v_fmac_f32_e32 v219, v200, v109
	v_fmac_f32_e32 v220, v181, v110
	v_fmac_f32_e32 v221, v201, v111
	v_fmac_f32_e32 v218, v184, v116
	v_fmac_f32_e32 v219, v204, v117
	v_fmac_f32_e32 v220, v185, v118
	v_fmac_f32_e32 v221, v205, v119
	v_lshlrev_b32_e32 v212, 16, v148
	v_and_b32_e32 v213, 0xffff0000, v148
	v_lshlrev_b32_e32 v214, 16, v149
	v_and_b32_e32 v215, 0xffff0000, v149
	v_mul_f32_e32 v218, v218, v212
	v_mul_f32_e32 v219, v219, v213
	v_mul_f32_e32 v220, v220, v214
	v_mul_f32_e32 v221, v221, v215
	v_cvt_pk_bf16_f32 v222, v218, v219
	v_cvt_pk_bf16_f32 v223, v220, v221
	global_store_dwordx2 v[100:101], v[222:223], off offset:1024
	v_lshl_add_u64 v[100:101], v[100:101], 0, s[42:43]
	s_waitcnt vmcnt(19)
	v_and_b32_e32 v213, 0xffff0000, v134
	v_lshlrev_b32_e32 v212, 16, v134
	v_mul_f32_e32 v208, v213, v213
	v_lshlrev_b32_e32 v214, 16, v135
	v_fmac_f32_e32 v208, v212, v212
	v_and_b32_e32 v215, 0xffff0000, v135
	v_fmac_f32_e32 v208, v214, v214
	v_fmac_f32_e32 v208, v215, v215
	v_lshlrev_b32_e32 v216, 16, v159
	v_and_b32_e32 v217, 0xffff0000, v159
	v_mul_f32_e32 v212, v216, v216
	v_mul_f32_e32 v213, v217, v217
	v_add_f32_e32 v209, v212, v213
	s_nop 0
	v_add_f32_dpp v208, v208, v208 quad_perm:[1,0,3,2] row_mask:0xf bank_mask:0xf
	v_add_f32_dpp v209, v209, v209 quad_perm:[1,0,3,2] row_mask:0xf bank_mask:0xf
	s_nop 0
	v_add_f32_dpp v208, v208, v208 quad_perm:[2,3,0,1] row_mask:0xf bank_mask:0xf
	v_add_f32_dpp v209, v209, v209 quad_perm:[2,3,0,1] row_mask:0xf bank_mask:0xf
	s_nop 0
	v_add_f32_dpp v208, v208, v208 row_half_mirror row_mask:0xf bank_mask:0xf
	v_add_f32_dpp v209, v209, v209 row_half_mirror row_mask:0xf bank_mask:0xf
	s_nop 0
	v_add_f32_dpp v208, v208, v208 row_mirror row_mask:0xf bank_mask:0xf
	v_add_f32_dpp v209, v209, v209 row_mirror row_mask:0xf bank_mask:0xf
	s_nop 0
	v_mov_b32_e32 v210, v208
	v_mov_b32_e32 v211, v209
	s_nop 1
	v_permlane32_swap_b32_e32 v208, v210
	v_permlane32_swap_b32_e32 v209, v211
	s_nop 0
	v_add_f32_e32 v208, v208, v210
	v_add_f32_e32 v209, v209, v211
	v_mov_b32_e32 v210, v208
	v_mov_b32_e32 v211, v209
	s_nop 1
	v_permlane16_swap_b32_e32 v208, v210
	v_permlane16_swap_b32_e32 v209, v211
	s_nop 0
	v_add_f32_e32 v208, v208, v210
	v_add_f32_e32 v209, v209, v211
	v_fmamk_f32 v159, v208, 0x3b800000, v48
	v_fmamk_f32 v209, v209, 0x3c000000, v48
	v_mul_f32_e32 v212, 0x4b800000, v209
	v_cmp_gt_f32_e64 s[6:7], s59, v209
	s_nop 1
	v_cndmask_b32_e64 v209, v209, v212, s[6:7]
	v_rsq_f32_e32 v209, v209
	s_nop 0
	v_mul_f32_e32 v212, 0x45800000, v209
	v_cndmask_b32_e64 v209, v209, v212, s[6:7]
	v_mul_f32_e32 v216, v209, v216
	v_mul_f32_e32 v217, v209, v217
	v_mul_f32_e32 v134, v106, v216
	v_mul_f32_e32 v135, v107, v217
	v_cvt_pk_bf16_f32 v212, v134, v135
	global_store_dword v[102:103], v212, off offset:1792
	s_waitcnt vmcnt(15)
	v_lshlrev_b32_e32 v224, 16, v186
	v_lshlrev_b32_e32 v225, 16, v206
	v_and_b32_e32 v186, 0xffff0000, v186
	v_and_b32_e32 v206, 0xffff0000, v206
	v_mul_f32_e32 v206, v186, v206
	v_mul_f32_e32 v186, v224, v225
	v_lshlrev_b32_e32 v224, 16, v187
	v_lshlrev_b32_e32 v225, 16, v207
	v_and_b32_e32 v187, 0xffff0000, v187
	v_and_b32_e32 v207, 0xffff0000, v207
	v_mul_f32_e32 v207, v187, v207
	v_mul_f32_e32 v187, v224, v225
	v_add_u32_e32 v226, 7, v67
	v_and_b32_e32 v226, 0xff, v226
	v_add_u32_e32 v227, 7, v68
	v_cndmask_b32_e64 v226, v227, v226, s[46:47]
	v_mov_b32_e32 v228, 0x7ff
	v_mov_b32_e32 v229, 0xff
	v_cndmask_b32_e64 v228, v228, v229, s[46:47]
	v_cmp_lt_u32_e32 vcc, v226, v228
	s_nop 1
	v_cndmask_b32_e32 v186, 0, v186, vcc
	v_cndmask_b32_e32 v206, 0, v206, vcc
	v_cndmask_b32_e32 v187, 0, v187, vcc
	v_cndmask_b32_e32 v207, 0, v207, vcc
	v_mul_f32_e32 v218, v184, v112
	v_mul_f32_e32 v219, v204, v113
	v_mul_f32_e32 v220, v185, v114
	v_mul_f32_e32 v221, v205, v115
	v_fmac_f32_e32 v218, v182, v108
	v_fmac_f32_e32 v219, v202, v109
	v_fmac_f32_e32 v220, v183, v110
	v_fmac_f32_e32 v221, v203, v111
	v_fmac_f32_e32 v218, v186, v116
	v_fmac_f32_e32 v219, v206, v117
	v_fmac_f32_e32 v220, v187, v118
	v_fmac_f32_e32 v221, v207, v119
	v_lshlrev_b32_e32 v212, 16, v150
	v_and_b32_e32 v213, 0xffff0000, v150
	v_lshlrev_b32_e32 v214, 16, v151
	v_and_b32_e32 v215, 0xffff0000, v151
	v_mul_f32_e32 v218, v218, v212
	v_mul_f32_e32 v219, v219, v213
	v_mul_f32_e32 v220, v220, v214
	v_mul_f32_e32 v221, v221, v215
	v_cvt_pk_bf16_f32 v222, v218, v219
	v_cvt_pk_bf16_f32 v223, v220, v221
	global_store_dwordx2 v[100:101], v[222:223], off offset:1024
	s_and_saveexec_b64 s[6:7], s[2:3]
	global_store_dword v[104:105], v152, off
	global_store_dword v[104:105], v153, off offset:4
	global_store_dword v[104:105], v154, off offset:8
	global_store_dword v[104:105], v155, off offset:12
	global_store_dword v[104:105], v156, off offset:16
	global_store_dword v[104:105], v157, off offset:20
	global_store_dword v[104:105], v158, off offset:24
	global_store_dword v[104:105], v159, off offset:28
	s_mov_b64 exec, s[6:7]
	s_and_saveexec_b64 s[6:7], s[46:47]
	s_cbranch_execz .Lcph_c0_noctx
	global_store_dwordx2 v[14:15], v[120:121], off
	global_store_dwordx2 v[14:15], v[122:123], off offset:512
	global_store_dwordx2 v[14:15], v[124:125], off offset:1024
	global_store_dwordx2 v[14:15], v[126:127], off offset:1536
	global_store_dwordx2 v[14:15], v[128:129], off offset:2048
	global_store_dwordx2 v[14:15], v[130:131], off offset:2560
	global_store_dwordx2 v[14:15], v[132:133], off offset:3072
	global_store_dwordx2 v[14:15], v[134:135], off offset:3584
	s_and_b64 exec, exec, s[4:5]
	v_lshlrev_b32_e32 v160, 16, v160
	v_lshlrev_b32_e32 v161, 16, v161
	v_lshlrev_b32_e32 v162, 16, v162
	v_lshlrev_b32_e32 v163, 16, v163
	v_lshlrev_b32_e32 v164, 16, v164
	v_lshlrev_b32_e32 v165, 16, v165
	v_lshlrev_b32_e32 v166, 16, v166
	v_lshlrev_b32_e32 v167, 16, v167
	global_store_dword v[12:13], v160, off
	global_store_dword v[12:13], v161, off offset:128
	global_store_dword v[12:13], v162, off offset:256
	global_store_dword v[12:13], v163, off offset:384
	global_store_dword v[12:13], v164, off offset:512
	global_store_dword v[12:13], v165, off offset:640
	global_store_dword v[12:13], v166, off offset:768
	global_store_dword v[12:13], v167, off offset:896
.Lcph_c0_noctx:
	s_mov_b64 exec, s[6:7]
	s_branch .LBB0_420

.LBB0_1666:
	s_mov_b32 s71, 8
	v_lshl_add_u64 v[94:95], s[14:15], 0, v[26:27]
	v_lshl_add_u64 v[96:97], s[14:15], 0, v[28:29]
	v_lshl_add_u64 v[98:99], s[14:15], 0, v[30:31]
	v_lshl_add_u64 v[100:101], s[14:15], 0, v[24:25]
	v_lshl_add_u64 v[104:105], s[14:15], 0, v[22:23]
	v_cmp_ge_i32_e64 s[50:51], s64, v20
	v_add_co_u32_e32 v94, vcc, 0x37f0000, v94
	s_nop 1
	v_addc_co_u32_e32 v95, vcc, 0, v95, vcc
	v_add_co_u32_e32 v100, vcc, s65, v100
	s_nop 1
	v_addc_co_u32_e32 v101, vcc, 0, v101, vcc
	s_and_b64 vcc, s[50:51], s[4:5]
	s_and_saveexec_b64 s[6:7], vcc
	s_cbranch_execz .Lcph_c1_nokpe
	global_load_ushort v160, v[98:99], off
	v_lshl_add_u64 v[98:99], v[98:99], 0, s[48:49]
	global_load_ushort v161, v[98:99], off
	v_lshl_add_u64 v[98:99], v[98:99], 0, s[48:49]
	global_load_ushort v162, v[98:99], off
	v_lshl_add_u64 v[98:99], v[98:99], 0, s[48:49]
	global_load_ushort v163, v[98:99], off
	v_lshl_add_u64 v[98:99], v[98:99], 0, s[48:49]
	global_load_ushort v164, v[98:99], off
	v_lshl_add_u64 v[98:99], v[98:99], 0, s[48:49]
	global_load_ushort v165, v[98:99], off
	v_lshl_add_u64 v[98:99], v[98:99], 0, s[48:49]
	global_load_ushort v166, v[98:99], off
	v_lshl_add_u64 v[98:99], v[98:99], 0, s[48:49]
	global_load_ushort v167, v[98:99], off
.Lcph_c1_nokpe:
	s_mov_b64 exec, s[6:7]
	global_load_dwordx2 v[106:107], v[6:7], off offset:512
	global_load_dwordx4 v[112:115], v[12:13], off
	global_load_dwordx4 v[108:111], v[10:11], off offset:3072
	global_load_dwordx4 v[116:119], v[14:15], off
	global_load_dwordx2 v[168:169], v[94:95], off offset:-3072
	global_load_dwordx2 v[188:189], v[94:95], off offset:-2560
	global_load_dwordx2 v[120:121], v[94:95], off
	global_load_dword v152, v[96:97], off
	global_load_dwordx2 v[136:137], v[94:95], off offset:832
	global_load_dwordx2 v[170:171], v[94:95], off offset:1344
	global_load_dwordx2 v[190:191], v[94:95], off offset:1856
	v_lshl_add_u64 v[94:95], v[94:95], 0, s[48:49]
	v_lshl_add_u64 v[96:97], v[96:97], 0, s[48:49]
	global_load_dwordx2 v[122:123], v[94:95], off
	global_load_dword v153, v[96:97], off
	global_load_dwordx2 v[138:139], v[94:95], off offset:832
	global_load_dwordx2 v[172:173], v[94:95], off offset:1344
	global_load_dwordx2 v[192:193], v[94:95], off offset:1856
	v_lshl_add_u64 v[94:95], v[94:95], 0, s[48:49]
	v_lshl_add_u64 v[96:97], v[96:97], 0, s[48:49]
	global_load_dwordx2 v[124:125], v[94:95], off
	global_load_dword v154, v[96:97], off
	global_load_dwordx2 v[140:141], v[94:95], off offset:832
	global_load_dwordx2 v[174:175], v[94:95], off offset:1344
	global_load_dwordx2 v[194:195], v[94:95], off offset:1856
	v_lshl_add_u64 v[94:95], v[94:95], 0, s[48:49]
	v_lshl_add_u64 v[96:97], v[96:97], 0, s[48:49]
	global_load_dwordx2 v[126:127], v[94:95], off
	global_load_dword v155, v[96:97], off
	global_load_dwordx2 v[142:143], v[94:95], off offset:832
	global_load_dwordx2 v[176:177], v[94:95], off offset:1344
	global_load_dwordx2 v[196:197], v[94:95], off offset:1856
	v_lshl_add_u64 v[94:95], v[94:95], 0, s[48:49]
	v_lshl_add_u64 v[96:97], v[96:97], 0, s[48:49]
	global_load_dwordx2 v[128:129], v[94:95], off
	global_load_dword v156, v[96:97], off
	global_load_dwordx2 v[144:145], v[94:95], off offset:832
	global_load_dwordx2 v[178:179], v[94:95], off offset:1344
	global_load_dwordx2 v[198:199], v[94:95], off offset:1856
	v_lshl_add_u64 v[94:95], v[94:95], 0, s[48:49]
	v_lshl_add_u64 v[96:97], v[96:97], 0, s[48:49]
	global_load_dwordx2 v[130:131], v[94:95], off
	global_load_dword v157, v[96:97], off
	global_load_dwordx2 v[146:147], v[94:95], off offset:832
	global_load_dwordx2 v[180:181], v[94:95], off offset:1344
	global_load_dwordx2 v[200:201], v[94:95], off offset:1856
	v_lshl_add_u64 v[94:95], v[94:95], 0, s[48:49]
	v_lshl_add_u64 v[96:97], v[96:97], 0, s[48:49]
	global_load_dwordx2 v[132:133], v[94:95], off
	global_load_dword v158, v[96:97], off
	global_load_dwordx2 v[148:149], v[94:95], off offset:832
	global_load_dwordx2 v[182:183], v[94:95], off offset:1344
	global_load_dwordx2 v[202:203], v[94:95], off offset:1856
	v_lshl_add_u64 v[94:95], v[94:95], 0, s[48:49]
	v_lshl_add_u64 v[96:97], v[96:97], 0, s[48:49]
	global_load_dwordx2 v[134:135], v[94:95], off
	global_load_dword v159, v[96:97], off
	global_load_dwordx2 v[150:151], v[94:95], off offset:832
	global_load_dwordx2 v[184:185], v[94:95], off offset:1344
	global_load_dwordx2 v[204:205], v[94:95], off offset:1856
	v_lshl_add_u64 v[94:95], v[94:95], 0, s[48:49]
	global_load_dwordx2 v[186:187], v[94:95], off offset:1344
	global_load_dwordx2 v[206:207], v[94:95], off offset:1856
	v_cndmask_b32_e64 v230, v70, 0, s[50:51]
	v_add_u32_e32 v230, v20, v230
	v_ashrrev_i32_e32 v231, 31, v230
	v_lshlrev_b64 v[102:103], 8, v[230:231]
	v_lshl_add_u64 v[102:103], v[8:9], 0, v[102:103]
	s_waitcnt vmcnt(40)
	v_and_b32_e32 v213, 0xffff0000, v120
	v_lshlrev_b32_e32 v212, 16, v120
	v_mul_f32_e32 v208, v213, v213
	v_lshlrev_b32_e32 v214, 16, v121
	v_fmac_f32_e32 v208, v212, v212
	v_and_b32_e32 v215, 0xffff0000, v121
	v_fmac_f32_e32 v208, v214, v214
	v_fmac_f32_e32 v208, v215, v215
	v_lshlrev_b32_e32 v216, 16, v152
	v_and_b32_e32 v217, 0xffff0000, v152
	v_mul_f32_e32 v212, v216, v216
	v_mul_f32_e32 v213, v217, v217
	v_add_f32_e32 v209, v212, v213
	s_nop 0
	v_add_f32_dpp v208, v208, v208 quad_perm:[1,0,3,2] row_mask:0xf bank_mask:0xf
	v_add_f32_dpp v209, v209, v209 quad_perm:[1,0,3,2] row_mask:0xf bank_mask:0xf
	s_nop 0
	v_add_f32_dpp v208, v208, v208 quad_perm:[2,3,0,1] row_mask:0xf bank_mask:0xf
	v_add_f32_dpp v209, v209, v209 quad_perm:[2,3,0,1] row_mask:0xf bank_mask:0xf
	s_nop 0
	v_add_f32_dpp v208, v208, v208 row_half_mirror row_mask:0xf bank_mask:0xf
	v_add_f32_dpp v209, v209, v209 row_half_mirror row_mask:0xf bank_mask:0xf
	s_nop 0
	v_add_f32_dpp v208, v208, v208 row_mirror row_mask:0xf bank_mask:0xf
	v_add_f32_dpp v209, v209, v209 row_mirror row_mask:0xf bank_mask:0xf
	s_nop 0
	v_mov_b32_e32 v210, v208
	v_mov_b32_e32 v211, v209
	s_nop 1
	v_permlane32_swap_b32_e32 v208, v210
	v_permlane32_swap_b32_e32 v209, v211
	s_nop 0
	v_add_f32_e32 v208, v208, v210
	v_add_f32_e32 v209, v209, v211
	v_mov_b32_e32 v210, v208
	v_mov_b32_e32 v211, v209
	s_nop 1
	v_permlane16_swap_b32_e32 v208, v210
	v_permlane16_swap_b32_e32 v209, v211
	s_nop 0
	v_add_f32_e32 v208, v208, v210
	v_add_f32_e32 v209, v209, v211
	v_fmamk_f32 v152, v208, 0x3b800000, v52
	v_fmamk_f32 v209, v209, 0x3c000000, v52
	v_mul_f32_e32 v212, 0x4b800000, v209
	v_cmp_gt_f32_e64 s[6:7], s63, v209
	s_nop 1
	v_cndmask_b32_e64 v209, v209, v212, s[6:7]
	v_rsq_f32_e32 v209, v209
	s_nop 0
	v_mul_f32_e32 v212, 0x45800000, v209
	v_cndmask_b32_e64 v209, v209, v212, s[6:7]
	v_mul_f32_e32 v216, v209, v216
	v_mul_f32_e32 v217, v209, v217
	v_mul_f32_e32 v120, v106, v216
	v_mul_f32_e32 v121, v107, v217
	v_cvt_pk_bf16_f32 v212, v120, v121
	global_store_dword v[102:103], v212, off
	s_waitcnt vmcnt(33)
	v_lshlrev_b32_e32 v224, 16, v168
	v_lshlrev_b32_e32 v225, 16, v188
	v_and_b32_e32 v168, 0xffff0000, v168
	v_and_b32_e32 v188, 0xffff0000, v188
	v_mul_f32_e32 v188, v168, v188
	v_mul_f32_e32 v168, v224, v225
	v_lshlrev_b32_e32 v224, 16, v169
	v_lshlrev_b32_e32 v225, 16, v189
	v_and_b32_e32 v169, 0xffff0000, v169
	v_and_b32_e32 v189, 0xffff0000, v189
	v_mul_f32_e32 v189, v169, v189
	v_mul_f32_e32 v169, v224, v225
	v_lshlrev_b32_e32 v224, 16, v170
	v_lshlrev_b32_e32 v225, 16, v190
	v_and_b32_e32 v170, 0xffff0000, v170
	v_and_b32_e32 v190, 0xffff0000, v190
	v_mul_f32_e32 v190, v170, v190
	v_mul_f32_e32 v170, v224, v225
	v_lshlrev_b32_e32 v224, 16, v171
	v_lshlrev_b32_e32 v225, 16, v191
	v_and_b32_e32 v171, 0xffff0000, v171
	v_and_b32_e32 v191, 0xffff0000, v191
	v_mul_f32_e32 v191, v171, v191
	v_mul_f32_e32 v171, v224, v225
	v_and_b32_e32 v226, 0xff, v71
	v_cndmask_b32_e64 v226, v72, v226, s[50:51]
	v_cmp_ne_u32_e32 vcc, 0, v226
	s_nop 1
	v_cndmask_b32_e32 v168, 0, v168, vcc
	v_cndmask_b32_e32 v188, 0, v188, vcc
	v_cndmask_b32_e32 v169, 0, v169, vcc
	v_cndmask_b32_e32 v189, 0, v189, vcc
	v_lshlrev_b32_e32 v224, 16, v172
	v_lshlrev_b32_e32 v225, 16, v192
	v_and_b32_e32 v172, 0xffff0000, v172
	v_and_b32_e32 v192, 0xffff0000, v192
	v_mul_f32_e32 v192, v172, v192
	v_mul_f32_e32 v172, v224, v225
	v_lshlrev_b32_e32 v224, 16, v173
	v_lshlrev_b32_e32 v225, 16, v193
	v_and_b32_e32 v173, 0xffff0000, v173
	v_and_b32_e32 v193, 0xffff0000, v193
	v_mul_f32_e32 v193, v173, v193
	v_mul_f32_e32 v173, v224, v225
	v_mul_f32_e32 v218, v170, v112
	v_mul_f32_e32 v219, v190, v113
	v_mul_f32_e32 v220, v171, v114
	v_mul_f32_e32 v221, v191, v115
	v_fmac_f32_e32 v218, v168, v108
	v_fmac_f32_e32 v219, v188, v109
	v_fmac_f32_e32 v220, v169, v110
	v_fmac_f32_e32 v221, v189, v111
	v_fmac_f32_e32 v218, v172, v116
	v_fmac_f32_e32 v219, v192, v117
	v_fmac_f32_e32 v220, v173, v118
	v_fmac_f32_e32 v221, v193, v119
	v_lshlrev_b32_e32 v212, 16, v136
	v_and_b32_e32 v213, 0xffff0000, v136
	v_lshlrev_b32_e32 v214, 16, v137
	v_and_b32_e32 v215, 0xffff0000, v137
	v_mul_f32_e32 v218, v218, v212
	v_mul_f32_e32 v219, v219, v213
	v_mul_f32_e32 v220, v220, v214
	v_mul_f32_e32 v221, v221, v215
	v_cvt_pk_bf16_f32 v222, v218, v219
	v_cvt_pk_bf16_f32 v223, v220, v221
	global_store_dwordx2 v[100:101], v[222:223], off offset:1024
	v_lshl_add_u64 v[100:101], v[100:101], 0, s[46:47]
	s_waitcnt vmcnt(37)
	v_and_b32_e32 v213, 0xffff0000, v122
	v_lshlrev_b32_e32 v212, 16, v122
	v_mul_f32_e32 v208, v213, v213
	v_lshlrev_b32_e32 v214, 16, v123
	v_fmac_f32_e32 v208, v212, v212
	v_and_b32_e32 v215, 0xffff0000, v123
	v_fmac_f32_e32 v208, v214, v214
	v_fmac_f32_e32 v208, v215, v215
	v_lshlrev_b32_e32 v216, 16, v153
	v_and_b32_e32 v217, 0xffff0000, v153
	v_mul_f32_e32 v212, v216, v216
	v_mul_f32_e32 v213, v217, v217
	v_add_f32_e32 v209, v212, v213
	s_nop 0
	v_add_f32_dpp v208, v208, v208 quad_perm:[1,0,3,2] row_mask:0xf bank_mask:0xf
	v_add_f32_dpp v209, v209, v209 quad_perm:[1,0,3,2] row_mask:0xf bank_mask:0xf
	s_nop 0
	v_add_f32_dpp v208, v208, v208 quad_perm:[2,3,0,1] row_mask:0xf bank_mask:0xf
	v_add_f32_dpp v209, v209, v209 quad_perm:[2,3,0,1] row_mask:0xf bank_mask:0xf
	s_nop 0
	v_add_f32_dpp v208, v208, v208 row_half_mirror row_mask:0xf bank_mask:0xf
	v_add_f32_dpp v209, v209, v209 row_half_mirror row_mask:0xf bank_mask:0xf
	s_nop 0
	v_add_f32_dpp v208, v208, v208 row_mirror row_mask:0xf bank_mask:0xf
	v_add_f32_dpp v209, v209, v209 row_mirror row_mask:0xf bank_mask:0xf
	s_nop 0
	v_mov_b32_e32 v210, v208
	v_mov_b32_e32 v211, v209
	s_nop 1
	v_permlane32_swap_b32_e32 v208, v210
	v_permlane32_swap_b32_e32 v209, v211
	s_nop 0
	v_add_f32_e32 v208, v208, v210
	v_add_f32_e32 v209, v209, v211
	v_mov_b32_e32 v210, v208
	v_mov_b32_e32 v211, v209
	s_nop 1
	v_permlane16_swap_b32_e32 v208, v210
	v_permlane16_swap_b32_e32 v209, v211
	s_nop 0
	v_add_f32_e32 v208, v208, v210
	v_add_f32_e32 v209, v209, v211
	v_fmamk_f32 v153, v208, 0x3b800000, v52
	v_fmamk_f32 v209, v209, 0x3c000000, v52
	v_mul_f32_e32 v212, 0x4b800000, v209
	v_cmp_gt_f32_e64 s[6:7], s63, v209
	s_nop 1
	v_cndmask_b32_e64 v209, v209, v212, s[6:7]
	v_rsq_f32_e32 v209, v209
	s_nop 0
	v_mul_f32_e32 v212, 0x45800000, v209
	v_cndmask_b32_e64 v209, v209, v212, s[6:7]
	v_mul_f32_e32 v216, v209, v216
	v_mul_f32_e32 v217, v209, v217
	v_mul_f32_e32 v122, v106, v216
	v_mul_f32_e32 v123, v107, v217
	v_cvt_pk_bf16_f32 v212, v122, v123
	global_store_dword v[102:103], v212, off offset:256
	s_waitcnt vmcnt(30)
	v_lshlrev_b32_e32 v224, 16, v174
	v_lshlrev_b32_e32 v225, 16, v194
	v_and_b32_e32 v174, 0xffff0000, v174
	v_and_b32_e32 v194, 0xffff0000, v194
	v_mul_f32_e32 v194, v174, v194
	v_mul_f32_e32 v174, v224, v225
	v_lshlrev_b32_e32 v224, 16, v175
	v_lshlrev_b32_e32 v225, 16, v195
	v_and_b32_e32 v175, 0xffff0000, v175
	v_and_b32_e32 v195, 0xffff0000, v195
	v_mul_f32_e32 v195, v175, v195
	v_mul_f32_e32 v175, v224, v225
	v_mul_f32_e32 v218, v172, v112
	v_mul_f32_e32 v219, v192, v113
	v_mul_f32_e32 v220, v173, v114
	v_mul_f32_e32 v221, v193, v115
	v_fmac_f32_e32 v218, v170, v108
	v_fmac_f32_e32 v219, v190, v109
	v_fmac_f32_e32 v220, v171, v110
	v_fmac_f32_e32 v221, v191, v111
	v_fmac_f32_e32 v218, v174, v116
	v_fmac_f32_e32 v219, v194, v117
	v_fmac_f32_e32 v220, v175, v118
	v_fmac_f32_e32 v221, v195, v119
	v_lshlrev_b32_e32 v212, 16, v138
	v_and_b32_e32 v213, 0xffff0000, v138
	v_lshlrev_b32_e32 v214, 16, v139
	v_and_b32_e32 v215, 0xffff0000, v139
	v_mul_f32_e32 v218, v218, v212
	v_mul_f32_e32 v219, v219, v213
	v_mul_f32_e32 v220, v220, v214
	v_mul_f32_e32 v221, v221, v215
	v_cvt_pk_bf16_f32 v222, v218, v219
	v_cvt_pk_bf16_f32 v223, v220, v221
	global_store_dwordx2 v[100:101], v[222:223], off offset:1024
	v_lshl_add_u64 v[100:101], v[100:101], 0, s[46:47]
	s_waitcnt vmcnt(34)
	v_and_b32_e32 v213, 0xffff0000, v124
	v_lshlrev_b32_e32 v212, 16, v124
	v_mul_f32_e32 v208, v213, v213
	v_lshlrev_b32_e32 v214, 16, v125
	v_fmac_f32_e32 v208, v212, v212
	v_and_b32_e32 v215, 0xffff0000, v125
	v_fmac_f32_e32 v208, v214, v214
	v_fmac_f32_e32 v208, v215, v215
	v_lshlrev_b32_e32 v216, 16, v154
	v_and_b32_e32 v217, 0xffff0000, v154
	v_mul_f32_e32 v212, v216, v216
	v_mul_f32_e32 v213, v217, v217
	v_add_f32_e32 v209, v212, v213
	s_nop 0
	v_add_f32_dpp v208, v208, v208 quad_perm:[1,0,3,2] row_mask:0xf bank_mask:0xf
	v_add_f32_dpp v209, v209, v209 quad_perm:[1,0,3,2] row_mask:0xf bank_mask:0xf
	s_nop 0
	v_add_f32_dpp v208, v208, v208 quad_perm:[2,3,0,1] row_mask:0xf bank_mask:0xf
	v_add_f32_dpp v209, v209, v209 quad_perm:[2,3,0,1] row_mask:0xf bank_mask:0xf
	s_nop 0
	v_add_f32_dpp v208, v208, v208 row_half_mirror row_mask:0xf bank_mask:0xf
	v_add_f32_dpp v209, v209, v209 row_half_mirror row_mask:0xf bank_mask:0xf
	s_nop 0
	v_add_f32_dpp v208, v208, v208 row_mirror row_mask:0xf bank_mask:0xf
	v_add_f32_dpp v209, v209, v209 row_mirror row_mask:0xf bank_mask:0xf
	s_nop 0
	v_mov_b32_e32 v210, v208
	v_mov_b32_e32 v211, v209
	s_nop 1
	v_permlane32_swap_b32_e32 v208, v210
	v_permlane32_swap_b32_e32 v209, v211
	s_nop 0
	v_add_f32_e32 v208, v208, v210
	v_add_f32_e32 v209, v209, v211
	v_mov_b32_e32 v210, v208
	v_mov_b32_e32 v211, v209
	s_nop 1
	v_permlane16_swap_b32_e32 v208, v210
	v_permlane16_swap_b32_e32 v209, v211
	s_nop 0
	v_add_f32_e32 v208, v208, v210
	v_add_f32_e32 v209, v209, v211
	v_fmamk_f32 v154, v208, 0x3b800000, v52
	v_fmamk_f32 v209, v209, 0x3c000000, v52
	v_mul_f32_e32 v212, 0x4b800000, v209
	v_cmp_gt_f32_e64 s[6:7], s63, v209
	s_nop 1
	v_cndmask_b32_e64 v209, v209, v212, s[6:7]
	v_rsq_f32_e32 v209, v209
	s_nop 0
	v_mul_f32_e32 v212, 0x45800000, v209
	v_cndmask_b32_e64 v209, v209, v212, s[6:7]
	v_mul_f32_e32 v216, v209, v216
	v_mul_f32_e32 v217, v209, v217
	v_mul_f32_e32 v124, v106, v216
	v_mul_f32_e32 v125, v107, v217
	v_cvt_pk_bf16_f32 v212, v124, v125
	global_store_dword v[102:103], v212, off offset:512
	s_waitcnt vmcnt(27)
	v_lshlrev_b32_e32 v224, 16, v176
	v_lshlrev_b32_e32 v225, 16, v196
	v_and_b32_e32 v176, 0xffff0000, v176
	v_and_b32_e32 v196, 0xffff0000, v196
	v_mul_f32_e32 v196, v176, v196
	v_mul_f32_e32 v176, v224, v225
	v_lshlrev_b32_e32 v224, 16, v177
	v_lshlrev_b32_e32 v225, 16, v197
	v_and_b32_e32 v177, 0xffff0000, v177
	v_and_b32_e32 v197, 0xffff0000, v197
	v_mul_f32_e32 v197, v177, v197
	v_mul_f32_e32 v177, v224, v225
	v_mul_f32_e32 v218, v174, v112
	v_mul_f32_e32 v219, v194, v113
	v_mul_f32_e32 v220, v175, v114
	v_mul_f32_e32 v221, v195, v115
	v_fmac_f32_e32 v218, v172, v108
	v_fmac_f32_e32 v219, v192, v109
	v_fmac_f32_e32 v220, v173, v110
	v_fmac_f32_e32 v221, v193, v111
	v_fmac_f32_e32 v218, v176, v116
	v_fmac_f32_e32 v219, v196, v117
	v_fmac_f32_e32 v220, v177, v118
	v_fmac_f32_e32 v221, v197, v119
	v_lshlrev_b32_e32 v212, 16, v140
	v_and_b32_e32 v213, 0xffff0000, v140
	v_lshlrev_b32_e32 v214, 16, v141
	v_and_b32_e32 v215, 0xffff0000, v141
	v_mul_f32_e32 v218, v218, v212
	v_mul_f32_e32 v219, v219, v213
	v_mul_f32_e32 v220, v220, v214
	v_mul_f32_e32 v221, v221, v215
	v_cvt_pk_bf16_f32 v222, v218, v219
	v_cvt_pk_bf16_f32 v223, v220, v221
	global_store_dwordx2 v[100:101], v[222:223], off offset:1024
	v_lshl_add_u64 v[100:101], v[100:101], 0, s[46:47]
	s_waitcnt vmcnt(31)
	v_and_b32_e32 v213, 0xffff0000, v126
	v_lshlrev_b32_e32 v212, 16, v126
	v_mul_f32_e32 v208, v213, v213
	v_lshlrev_b32_e32 v214, 16, v127
	v_fmac_f32_e32 v208, v212, v212
	v_and_b32_e32 v215, 0xffff0000, v127
	v_fmac_f32_e32 v208, v214, v214
	v_fmac_f32_e32 v208, v215, v215
	v_lshlrev_b32_e32 v216, 16, v155
	v_and_b32_e32 v217, 0xffff0000, v155
	v_mul_f32_e32 v212, v216, v216
	v_mul_f32_e32 v213, v217, v217
	v_add_f32_e32 v209, v212, v213
	s_nop 0
	v_add_f32_dpp v208, v208, v208 quad_perm:[1,0,3,2] row_mask:0xf bank_mask:0xf
	v_add_f32_dpp v209, v209, v209 quad_perm:[1,0,3,2] row_mask:0xf bank_mask:0xf
	s_nop 0
	v_add_f32_dpp v208, v208, v208 quad_perm:[2,3,0,1] row_mask:0xf bank_mask:0xf
	v_add_f32_dpp v209, v209, v209 quad_perm:[2,3,0,1] row_mask:0xf bank_mask:0xf
	s_nop 0
	v_add_f32_dpp v208, v208, v208 row_half_mirror row_mask:0xf bank_mask:0xf
	v_add_f32_dpp v209, v209, v209 row_half_mirror row_mask:0xf bank_mask:0xf
	s_nop 0
	v_add_f32_dpp v208, v208, v208 row_mirror row_mask:0xf bank_mask:0xf
	v_add_f32_dpp v209, v209, v209 row_mirror row_mask:0xf bank_mask:0xf
	s_nop 0
	v_mov_b32_e32 v210, v208
	v_mov_b32_e32 v211, v209
	s_nop 1
	v_permlane32_swap_b32_e32 v208, v210
	v_permlane32_swap_b32_e32 v209, v211
	s_nop 0
	v_add_f32_e32 v208, v208, v210
	v_add_f32_e32 v209, v209, v211
	v_mov_b32_e32 v210, v208
	v_mov_b32_e32 v211, v209
	s_nop 1
	v_permlane16_swap_b32_e32 v208, v210
	v_permlane16_swap_b32_e32 v209, v211
	s_nop 0
	v_add_f32_e32 v208, v208, v210
	v_add_f32_e32 v209, v209, v211
	v_fmamk_f32 v155, v208, 0x3b800000, v52
	v_fmamk_f32 v209, v209, 0x3c000000, v52
	v_mul_f32_e32 v212, 0x4b800000, v209
	v_cmp_gt_f32_e64 s[6:7], s63, v209
	s_nop 1
	v_cndmask_b32_e64 v209, v209, v212, s[6:7]
	v_rsq_f32_e32 v209, v209
	s_nop 0
	v_mul_f32_e32 v212, 0x45800000, v209
	v_cndmask_b32_e64 v209, v209, v212, s[6:7]
	v_mul_f32_e32 v216, v209, v216
	v_mul_f32_e32 v217, v209, v217
	v_mul_f32_e32 v126, v106, v216
	v_mul_f32_e32 v127, v107, v217
	v_cvt_pk_bf16_f32 v212, v126, v127
	global_store_dword v[102:103], v212, off offset:768
	s_waitcnt vmcnt(24)
	v_lshlrev_b32_e32 v224, 16, v178
	v_lshlrev_b32_e32 v225, 16, v198
	v_and_b32_e32 v178, 0xffff0000, v178
	v_and_b32_e32 v198, 0xffff0000, v198
	v_mul_f32_e32 v198, v178, v198
	v_mul_f32_e32 v178, v224, v225
	v_lshlrev_b32_e32 v224, 16, v179
	v_lshlrev_b32_e32 v225, 16, v199
	v_and_b32_e32 v179, 0xffff0000, v179
	v_and_b32_e32 v199, 0xffff0000, v199
	v_mul_f32_e32 v199, v179, v199
	v_mul_f32_e32 v179, v224, v225
	v_mul_f32_e32 v218, v176, v112
	v_mul_f32_e32 v219, v196, v113
	v_mul_f32_e32 v220, v177, v114
	v_mul_f32_e32 v221, v197, v115
	v_fmac_f32_e32 v218, v174, v108
	v_fmac_f32_e32 v219, v194, v109
	v_fmac_f32_e32 v220, v175, v110
	v_fmac_f32_e32 v221, v195, v111
	v_fmac_f32_e32 v218, v178, v116
	v_fmac_f32_e32 v219, v198, v117
	v_fmac_f32_e32 v220, v179, v118
	v_fmac_f32_e32 v221, v199, v119
	v_lshlrev_b32_e32 v212, 16, v142
	v_and_b32_e32 v213, 0xffff0000, v142
	v_lshlrev_b32_e32 v214, 16, v143
	v_and_b32_e32 v215, 0xffff0000, v143
	v_mul_f32_e32 v218, v218, v212
	v_mul_f32_e32 v219, v219, v213
	v_mul_f32_e32 v220, v220, v214
	v_mul_f32_e32 v221, v221, v215
	v_cvt_pk_bf16_f32 v222, v218, v219
	v_cvt_pk_bf16_f32 v223, v220, v221
	global_store_dwordx2 v[100:101], v[222:223], off offset:1024
	v_lshl_add_u64 v[100:101], v[100:101], 0, s[46:47]
	s_waitcnt vmcnt(28)
	v_and_b32_e32 v213, 0xffff0000, v128
	v_lshlrev_b32_e32 v212, 16, v128
	v_mul_f32_e32 v208, v213, v213
	v_lshlrev_b32_e32 v214, 16, v129
	v_fmac_f32_e32 v208, v212, v212
	v_and_b32_e32 v215, 0xffff0000, v129
	v_fmac_f32_e32 v208, v214, v214
	v_fmac_f32_e32 v208, v215, v215
	v_lshlrev_b32_e32 v216, 16, v156
	v_and_b32_e32 v217, 0xffff0000, v156
	v_mul_f32_e32 v212, v216, v216
	v_mul_f32_e32 v213, v217, v217
	v_add_f32_e32 v209, v212, v213
	s_nop 0
	v_add_f32_dpp v208, v208, v208 quad_perm:[1,0,3,2] row_mask:0xf bank_mask:0xf
	v_add_f32_dpp v209, v209, v209 quad_perm:[1,0,3,2] row_mask:0xf bank_mask:0xf
	s_nop 0
	v_add_f32_dpp v208, v208, v208 quad_perm:[2,3,0,1] row_mask:0xf bank_mask:0xf
	v_add_f32_dpp v209, v209, v209 quad_perm:[2,3,0,1] row_mask:0xf bank_mask:0xf
	s_nop 0
	v_add_f32_dpp v208, v208, v208 row_half_mirror row_mask:0xf bank_mask:0xf
	v_add_f32_dpp v209, v209, v209 row_half_mirror row_mask:0xf bank_mask:0xf
	s_nop 0
	v_add_f32_dpp v208, v208, v208 row_mirror row_mask:0xf bank_mask:0xf
	v_add_f32_dpp v209, v209, v209 row_mirror row_mask:0xf bank_mask:0xf
	s_nop 0
	v_mov_b32_e32 v210, v208
	v_mov_b32_e32 v211, v209
	s_nop 1
	v_permlane32_swap_b32_e32 v208, v210
	v_permlane32_swap_b32_e32 v209, v211
	s_nop 0
	v_add_f32_e32 v208, v208, v210
	v_add_f32_e32 v209, v209, v211
	v_mov_b32_e32 v210, v208
	v_mov_b32_e32 v211, v209
	s_nop 1
	v_permlane16_swap_b32_e32 v208, v210
	v_permlane16_swap_b32_e32 v209, v211
	s_nop 0
	v_add_f32_e32 v208, v208, v210
	v_add_f32_e32 v209, v209, v211
	v_fmamk_f32 v156, v208, 0x3b800000, v52
	v_fmamk_f32 v209, v209, 0x3c000000, v52
	v_mul_f32_e32 v212, 0x4b800000, v209
	v_cmp_gt_f32_e64 s[6:7], s63, v209
	s_nop 1
	v_cndmask_b32_e64 v209, v209, v212, s[6:7]
	v_rsq_f32_e32 v209, v209
	s_nop 0
	v_mul_f32_e32 v212, 0x45800000, v209
	v_cndmask_b32_e64 v209, v209, v212, s[6:7]
	v_mul_f32_e32 v216, v209, v216
	v_mul_f32_e32 v217, v209, v217
	v_mul_f32_e32 v128, v106, v216
	v_mul_f32_e32 v129, v107, v217
	v_cvt_pk_bf16_f32 v212, v128, v129
	global_store_dword v[102:103], v212, off offset:1024
	s_waitcnt vmcnt(21)
	v_lshlrev_b32_e32 v224, 16, v180
	v_lshlrev_b32_e32 v225, 16, v200
	v_and_b32_e32 v180, 0xffff0000, v180
	v_and_b32_e32 v200, 0xffff0000, v200
	v_mul_f32_e32 v200, v180, v200
	v_mul_f32_e32 v180, v224, v225
	v_lshlrev_b32_e32 v224, 16, v181
	v_lshlrev_b32_e32 v225, 16, v201
	v_and_b32_e32 v181, 0xffff0000, v181
	v_and_b32_e32 v201, 0xffff0000, v201
	v_mul_f32_e32 v201, v181, v201
	v_mul_f32_e32 v181, v224, v225
	v_mul_f32_e32 v218, v178, v112
	v_mul_f32_e32 v219, v198, v113
	v_mul_f32_e32 v220, v179, v114
	v_mul_f32_e32 v221, v199, v115
	v_fmac_f32_e32 v218, v176, v108
	v_fmac_f32_e32 v219, v196, v109
	v_fmac_f32_e32 v220, v177, v110
	v_fmac_f32_e32 v221, v197, v111
	v_fmac_f32_e32 v218, v180, v116
	v_fmac_f32_e32 v219, v200, v117
	v_fmac_f32_e32 v220, v181, v118
	v_fmac_f32_e32 v221, v201, v119
	v_lshlrev_b32_e32 v212, 16, v144
	v_and_b32_e32 v213, 0xffff0000, v144
	v_lshlrev_b32_e32 v214, 16, v145
	v_and_b32_e32 v215, 0xffff0000, v145
	v_mul_f32_e32 v218, v218, v212
	v_mul_f32_e32 v219, v219, v213
	v_mul_f32_e32 v220, v220, v214
	v_mul_f32_e32 v221, v221, v215
	v_cvt_pk_bf16_f32 v222, v218, v219
	v_cvt_pk_bf16_f32 v223, v220, v221
	global_store_dwordx2 v[100:101], v[222:223], off offset:1024
	v_lshl_add_u64 v[100:101], v[100:101], 0, s[46:47]
	s_waitcnt vmcnt(25)
	v_and_b32_e32 v213, 0xffff0000, v130
	v_lshlrev_b32_e32 v212, 16, v130
	v_mul_f32_e32 v208, v213, v213
	v_lshlrev_b32_e32 v214, 16, v131
	v_fmac_f32_e32 v208, v212, v212
	v_and_b32_e32 v215, 0xffff0000, v131
	v_fmac_f32_e32 v208, v214, v214
	v_fmac_f32_e32 v208, v215, v215
	v_lshlrev_b32_e32 v216, 16, v157
	v_and_b32_e32 v217, 0xffff0000, v157
	v_mul_f32_e32 v212, v216, v216
	v_mul_f32_e32 v213, v217, v217
	v_add_f32_e32 v209, v212, v213
	s_nop 0
	v_add_f32_dpp v208, v208, v208 quad_perm:[1,0,3,2] row_mask:0xf bank_mask:0xf
	v_add_f32_dpp v209, v209, v209 quad_perm:[1,0,3,2] row_mask:0xf bank_mask:0xf
	s_nop 0
	v_add_f32_dpp v208, v208, v208 quad_perm:[2,3,0,1] row_mask:0xf bank_mask:0xf
	v_add_f32_dpp v209, v209, v209 quad_perm:[2,3,0,1] row_mask:0xf bank_mask:0xf
	s_nop 0
	v_add_f32_dpp v208, v208, v208 row_half_mirror row_mask:0xf bank_mask:0xf
	v_add_f32_dpp v209, v209, v209 row_half_mirror row_mask:0xf bank_mask:0xf
	s_nop 0
	v_add_f32_dpp v208, v208, v208 row_mirror row_mask:0xf bank_mask:0xf
	v_add_f32_dpp v209, v209, v209 row_mirror row_mask:0xf bank_mask:0xf
	s_nop 0
	v_mov_b32_e32 v210, v208
	v_mov_b32_e32 v211, v209
	s_nop 1
	v_permlane32_swap_b32_e32 v208, v210
	v_permlane32_swap_b32_e32 v209, v211
	s_nop 0
	v_add_f32_e32 v208, v208, v210
	v_add_f32_e32 v209, v209, v211
	v_mov_b32_e32 v210, v208
	v_mov_b32_e32 v211, v209
	s_nop 1
	v_permlane16_swap_b32_e32 v208, v210
	v_permlane16_swap_b32_e32 v209, v211
	s_nop 0
	v_add_f32_e32 v208, v208, v210
	v_add_f32_e32 v209, v209, v211
	v_fmamk_f32 v157, v208, 0x3b800000, v52
	v_fmamk_f32 v209, v209, 0x3c000000, v52
	v_mul_f32_e32 v212, 0x4b800000, v209
	v_cmp_gt_f32_e64 s[6:7], s63, v209
	s_nop 1
	v_cndmask_b32_e64 v209, v209, v212, s[6:7]
	v_rsq_f32_e32 v209, v209
	s_nop 0
	v_mul_f32_e32 v212, 0x45800000, v209
	v_cndmask_b32_e64 v209, v209, v212, s[6:7]
	v_mul_f32_e32 v216, v209, v216
	v_mul_f32_e32 v217, v209, v217
	v_mul_f32_e32 v130, v106, v216
	v_mul_f32_e32 v131, v107, v217
	v_cvt_pk_bf16_f32 v212, v130, v131
	global_store_dword v[102:103], v212, off offset:1280
	s_waitcnt vmcnt(18)
	v_lshlrev_b32_e32 v224, 16, v182
	v_lshlrev_b32_e32 v225, 16, v202
	v_and_b32_e32 v182, 0xffff0000, v182
	v_and_b32_e32 v202, 0xffff0000, v202
	v_mul_f32_e32 v202, v182, v202
	v_mul_f32_e32 v182, v224, v225
	v_lshlrev_b32_e32 v224, 16, v183
	v_lshlrev_b32_e32 v225, 16, v203
	v_and_b32_e32 v183, 0xffff0000, v183
	v_and_b32_e32 v203, 0xffff0000, v203
	v_mul_f32_e32 v203, v183, v203
	v_mul_f32_e32 v183, v224, v225
	v_mul_f32_e32 v218, v180, v112
	v_mul_f32_e32 v219, v200, v113
	v_mul_f32_e32 v220, v181, v114
	v_mul_f32_e32 v221, v201, v115
	v_fmac_f32_e32 v218, v178, v108
	v_fmac_f32_e32 v219, v198, v109
	v_fmac_f32_e32 v220, v179, v110
	v_fmac_f32_e32 v221, v199, v111
	v_fmac_f32_e32 v218, v182, v116
	v_fmac_f32_e32 v219, v202, v117
	v_fmac_f32_e32 v220, v183, v118
	v_fmac_f32_e32 v221, v203, v119
	v_lshlrev_b32_e32 v212, 16, v146
	v_and_b32_e32 v213, 0xffff0000, v146
	v_lshlrev_b32_e32 v214, 16, v147
	v_and_b32_e32 v215, 0xffff0000, v147
	v_mul_f32_e32 v218, v218, v212
	v_mul_f32_e32 v219, v219, v213
	v_mul_f32_e32 v220, v220, v214
	v_mul_f32_e32 v221, v221, v215
	v_cvt_pk_bf16_f32 v222, v218, v219
	v_cvt_pk_bf16_f32 v223, v220, v221
	global_store_dwordx2 v[100:101], v[222:223], off offset:1024
	v_lshl_add_u64 v[100:101], v[100:101], 0, s[46:47]
	s_waitcnt vmcnt(22)
	v_and_b32_e32 v213, 0xffff0000, v132
	v_lshlrev_b32_e32 v212, 16, v132
	v_mul_f32_e32 v208, v213, v213
	v_lshlrev_b32_e32 v214, 16, v133
	v_fmac_f32_e32 v208, v212, v212
	v_and_b32_e32 v215, 0xffff0000, v133
	v_fmac_f32_e32 v208, v214, v214
	v_fmac_f32_e32 v208, v215, v215
	v_lshlrev_b32_e32 v216, 16, v158
	v_and_b32_e32 v217, 0xffff0000, v158
	v_mul_f32_e32 v212, v216, v216
	v_mul_f32_e32 v213, v217, v217
	v_add_f32_e32 v209, v212, v213
	s_nop 0
	v_add_f32_dpp v208, v208, v208 quad_perm:[1,0,3,2] row_mask:0xf bank_mask:0xf
	v_add_f32_dpp v209, v209, v209 quad_perm:[1,0,3,2] row_mask:0xf bank_mask:0xf
	s_nop 0
	v_add_f32_dpp v208, v208, v208 quad_perm:[2,3,0,1] row_mask:0xf bank_mask:0xf
	v_add_f32_dpp v209, v209, v209 quad_perm:[2,3,0,1] row_mask:0xf bank_mask:0xf
	s_nop 0
	v_add_f32_dpp v208, v208, v208 row_half_mirror row_mask:0xf bank_mask:0xf
	v_add_f32_dpp v209, v209, v209 row_half_mirror row_mask:0xf bank_mask:0xf
	s_nop 0
	v_add_f32_dpp v208, v208, v208 row_mirror row_mask:0xf bank_mask:0xf
	v_add_f32_dpp v209, v209, v209 row_mirror row_mask:0xf bank_mask:0xf
	s_nop 0
	v_mov_b32_e32 v210, v208
	v_mov_b32_e32 v211, v209
	s_nop 1
	v_permlane32_swap_b32_e32 v208, v210
	v_permlane32_swap_b32_e32 v209, v211
	s_nop 0
	v_add_f32_e32 v208, v208, v210
	v_add_f32_e32 v209, v209, v211
	v_mov_b32_e32 v210, v208
	v_mov_b32_e32 v211, v209
	s_nop 1
	v_permlane16_swap_b32_e32 v208, v210
	v_permlane16_swap_b32_e32 v209, v211
	s_nop 0
	v_add_f32_e32 v208, v208, v210
	v_add_f32_e32 v209, v209, v211
	v_fmamk_f32 v158, v208, 0x3b800000, v52
	v_fmamk_f32 v209, v209, 0x3c000000, v52
	v_mul_f32_e32 v212, 0x4b800000, v209
	v_cmp_gt_f32_e64 s[6:7], s63, v209
	s_nop 1
	v_cndmask_b32_e64 v209, v209, v212, s[6:7]
	v_rsq_f32_e32 v209, v209
	s_nop 0
	v_mul_f32_e32 v212, 0x45800000, v209
	v_cndmask_b32_e64 v209, v209, v212, s[6:7]
	v_mul_f32_e32 v216, v209, v216
	v_mul_f32_e32 v217, v209, v217
	v_mul_f32_e32 v132, v106, v216
	v_mul_f32_e32 v133, v107, v217
	v_cvt_pk_bf16_f32 v212, v132, v133
	global_store_dword v[102:103], v212, off offset:1536
	s_waitcnt vmcnt(15)
	v_lshlrev_b32_e32 v224, 16, v184
	v_lshlrev_b32_e32 v225, 16, v204
	v_and_b32_e32 v184, 0xffff0000, v184
	v_and_b32_e32 v204, 0xffff0000, v204
	v_mul_f32_e32 v204, v184, v204
	v_mul_f32_e32 v184, v224, v225
	v_lshlrev_b32_e32 v224, 16, v185
	v_lshlrev_b32_e32 v225, 16, v205
	v_and_b32_e32 v185, 0xffff0000, v185
	v_and_b32_e32 v205, 0xffff0000, v205
	v_mul_f32_e32 v205, v185, v205
	v_mul_f32_e32 v185, v224, v225
	v_mul_f32_e32 v218, v182, v112
	v_mul_f32_e32 v219, v202, v113
	v_mul_f32_e32 v220, v183, v114
	v_mul_f32_e32 v221, v203, v115
	v_fmac_f32_e32 v218, v180, v108
	v_fmac_f32_e32 v219, v200, v109
	v_fmac_f32_e32 v220, v181, v110
	v_fmac_f32_e32 v221, v201, v111
	v_fmac_f32_e32 v218, v184, v116
	v_fmac_f32_e32 v219, v204, v117
	v_fmac_f32_e32 v220, v185, v118
	v_fmac_f32_e32 v221, v205, v119
	v_lshlrev_b32_e32 v212, 16, v148
	v_and_b32_e32 v213, 0xffff0000, v148
	v_lshlrev_b32_e32 v214, 16, v149
	v_and_b32_e32 v215, 0xffff0000, v149
	v_mul_f32_e32 v218, v218, v212
	v_mul_f32_e32 v219, v219, v213
	v_mul_f32_e32 v220, v220, v214
	v_mul_f32_e32 v221, v221, v215
	v_cvt_pk_bf16_f32 v222, v218, v219
	v_cvt_pk_bf16_f32 v223, v220, v221
	global_store_dwordx2 v[100:101], v[222:223], off offset:1024
	v_lshl_add_u64 v[100:101], v[100:101], 0, s[46:47]
	s_waitcnt vmcnt(19)
	v_and_b32_e32 v213, 0xffff0000, v134
	v_lshlrev_b32_e32 v212, 16, v134
	v_mul_f32_e32 v208, v213, v213
	v_lshlrev_b32_e32 v214, 16, v135
	v_fmac_f32_e32 v208, v212, v212
	v_and_b32_e32 v215, 0xffff0000, v135
	v_fmac_f32_e32 v208, v214, v214
	v_fmac_f32_e32 v208, v215, v215
	v_lshlrev_b32_e32 v216, 16, v159
	v_and_b32_e32 v217, 0xffff0000, v159
	v_mul_f32_e32 v212, v216, v216
	v_mul_f32_e32 v213, v217, v217
	v_add_f32_e32 v209, v212, v213
	s_nop 0
	v_add_f32_dpp v208, v208, v208 quad_perm:[1,0,3,2] row_mask:0xf bank_mask:0xf
	v_add_f32_dpp v209, v209, v209 quad_perm:[1,0,3,2] row_mask:0xf bank_mask:0xf
	s_nop 0
	v_add_f32_dpp v208, v208, v208 quad_perm:[2,3,0,1] row_mask:0xf bank_mask:0xf
	v_add_f32_dpp v209, v209, v209 quad_perm:[2,3,0,1] row_mask:0xf bank_mask:0xf
	s_nop 0
	v_add_f32_dpp v208, v208, v208 row_half_mirror row_mask:0xf bank_mask:0xf
	v_add_f32_dpp v209, v209, v209 row_half_mirror row_mask:0xf bank_mask:0xf
	s_nop 0
	v_add_f32_dpp v208, v208, v208 row_mirror row_mask:0xf bank_mask:0xf
	v_add_f32_dpp v209, v209, v209 row_mirror row_mask:0xf bank_mask:0xf
	s_nop 0
	v_mov_b32_e32 v210, v208
	v_mov_b32_e32 v211, v209
	s_nop 1
	v_permlane32_swap_b32_e32 v208, v210
	v_permlane32_swap_b32_e32 v209, v211
	s_nop 0
	v_add_f32_e32 v208, v208, v210
	v_add_f32_e32 v209, v209, v211
	v_mov_b32_e32 v210, v208
	v_mov_b32_e32 v211, v209
	s_nop 1
	v_permlane16_swap_b32_e32 v208, v210
	v_permlane16_swap_b32_e32 v209, v211
	s_nop 0
	v_add_f32_e32 v208, v208, v210
	v_add_f32_e32 v209, v209, v211
	v_fmamk_f32 v159, v208, 0x3b800000, v52
	v_fmamk_f32 v209, v209, 0x3c000000, v52
	v_mul_f32_e32 v212, 0x4b800000, v209
	v_cmp_gt_f32_e64 s[6:7], s63, v209
	s_nop 1
	v_cndmask_b32_e64 v209, v209, v212, s[6:7]
	v_rsq_f32_e32 v209, v209
	s_nop 0
	v_mul_f32_e32 v212, 0x45800000, v209
	v_cndmask_b32_e64 v209, v209, v212, s[6:7]
	v_mul_f32_e32 v216, v209, v216
	v_mul_f32_e32 v217, v209, v217
	v_mul_f32_e32 v134, v106, v216
	v_mul_f32_e32 v135, v107, v217
	v_cvt_pk_bf16_f32 v212, v134, v135
	global_store_dword v[102:103], v212, off offset:1792
	s_waitcnt vmcnt(15)
	v_lshlrev_b32_e32 v224, 16, v186
	v_lshlrev_b32_e32 v225, 16, v206
	v_and_b32_e32 v186, 0xffff0000, v186
	v_and_b32_e32 v206, 0xffff0000, v206
	v_mul_f32_e32 v206, v186, v206
	v_mul_f32_e32 v186, v224, v225
	v_lshlrev_b32_e32 v224, 16, v187
	v_lshlrev_b32_e32 v225, 16, v207
	v_and_b32_e32 v187, 0xffff0000, v187
	v_and_b32_e32 v207, 0xffff0000, v207
	v_mul_f32_e32 v207, v187, v207
	v_mul_f32_e32 v187, v224, v225
	v_add_u32_e32 v226, 7, v71
	v_and_b32_e32 v226, 0xff, v226
	v_add_u32_e32 v227, 7, v72
	v_cndmask_b32_e64 v226, v227, v226, s[50:51]
	v_mov_b32_e32 v228, 0x7ff
	v_mov_b32_e32 v229, 0xff
	v_cndmask_b32_e64 v228, v228, v229, s[50:51]
	v_cmp_lt_u32_e32 vcc, v226, v228
	s_nop 1
	v_cndmask_b32_e32 v186, 0, v186, vcc
	v_cndmask_b32_e32 v206, 0, v206, vcc
	v_cndmask_b32_e32 v187, 0, v187, vcc
	v_cndmask_b32_e32 v207, 0, v207, vcc
	v_mul_f32_e32 v218, v184, v112
	v_mul_f32_e32 v219, v204, v113
	v_mul_f32_e32 v220, v185, v114
	v_mul_f32_e32 v221, v205, v115
	v_fmac_f32_e32 v218, v182, v108
	v_fmac_f32_e32 v219, v202, v109
	v_fmac_f32_e32 v220, v183, v110
	v_fmac_f32_e32 v221, v203, v111
	v_fmac_f32_e32 v218, v186, v116
	v_fmac_f32_e32 v219, v206, v117
	v_fmac_f32_e32 v220, v187, v118
	v_fmac_f32_e32 v221, v207, v119
	v_lshlrev_b32_e32 v212, 16, v150
	v_and_b32_e32 v213, 0xffff0000, v150
	v_lshlrev_b32_e32 v214, 16, v151
	v_and_b32_e32 v215, 0xffff0000, v151
	v_mul_f32_e32 v218, v218, v212
	v_mul_f32_e32 v219, v219, v213
	v_mul_f32_e32 v220, v220, v214
	v_mul_f32_e32 v221, v221, v215
	v_cvt_pk_bf16_f32 v222, v218, v219
	v_cvt_pk_bf16_f32 v223, v220, v221
	global_store_dwordx2 v[100:101], v[222:223], off offset:1024
	s_and_saveexec_b64 s[6:7], s[2:3]
	global_store_dword v[104:105], v152, off
	global_store_dword v[104:105], v153, off offset:4
	global_store_dword v[104:105], v154, off offset:8
	global_store_dword v[104:105], v155, off offset:12
	global_store_dword v[104:105], v156, off offset:16
	global_store_dword v[104:105], v157, off offset:20
	global_store_dword v[104:105], v158, off offset:24
	global_store_dword v[104:105], v159, off offset:28
	s_mov_b64 exec, s[6:7]
	s_and_saveexec_b64 s[6:7], s[50:51]
	s_cbranch_execz .Lcph_c1_noctx
	global_store_dwordx2 v[18:19], v[120:121], off
	global_store_dwordx2 v[18:19], v[122:123], off offset:512
	global_store_dwordx2 v[18:19], v[124:125], off offset:1024
	global_store_dwordx2 v[18:19], v[126:127], off offset:1536
	global_store_dwordx2 v[18:19], v[128:129], off offset:2048
	global_store_dwordx2 v[18:19], v[130:131], off offset:2560
	global_store_dwordx2 v[18:19], v[132:133], off offset:3072
	global_store_dwordx2 v[18:19], v[134:135], off offset:3584
	s_and_b64 exec, exec, s[4:5]
	v_lshlrev_b32_e32 v160, 16, v160
	v_lshlrev_b32_e32 v161, 16, v161
	v_lshlrev_b32_e32 v162, 16, v162
	v_lshlrev_b32_e32 v163, 16, v163
	v_lshlrev_b32_e32 v164, 16, v164
	v_lshlrev_b32_e32 v165, 16, v165
	v_lshlrev_b32_e32 v166, 16, v166
	v_lshlrev_b32_e32 v167, 16, v167
	global_store_dword v[16:17], v160, off
	global_store_dword v[16:17], v161, off offset:128
	global_store_dword v[16:17], v162, off offset:256
	global_store_dword v[16:17], v163, off offset:384
	global_store_dword v[16:17], v164, off offset:512
	global_store_dword v[16:17], v165, off offset:640
	global_store_dword v[16:17], v166, off offset:768
	global_store_dword v[16:17], v167, off offset:896
